# la_unit MFMA loads pipelined; group-barrier L1 invalidate issued ahead of the opening barrier (argument: no phase reads lines another WG writes in the same phase)
# baseline (speedup 1.0000x reference)
; #define LAS __attribute__((address_space(3)))
; DI float xsum16(float v) { const unsigned u = __float_as_uint(v); const u32x2p r = __builtin_amdgcn_permlane16_swap(u, u, false, false); return __uint_as_float(r[0]) + __uint_as_float(r[1]); }
; DI float xsum32(float v) { const unsigned u = __float_as_uint(v); const u32x2p r = __builtin_amdgcn_permlane32_swap(u, u, false, false); return __uint_as_float(r[0]) + __uint_as_float(r[1]); }
; DI float rs_of_row(const float* SS, int row, int fq) {
;     const f32x4 a = *(const f32x4*)(SS + (size_t)row * 32 + 8 * fq), b = *(const f32x4*)(SS + (size_t)row * 32 + 8 * fq + 4);
;     float s = ((a[0] + a[1]) + (a[2] + a[3])) + ((b[0] + b[1]) + (b[2] + b[3]));
;     s = xsum32(xsum16(s));
;     return __builtin_amdgcn_rsqf(s * (1.0f / 1024.0f) + RMS_EPS);
; DI void la_unit(const bf16* __restrict__ XB, const bf16* __restrict__ W16, const float* SS, const float* __restrict__ wa2, const float* __restrict__ ba, float* __restrict__ LA, LAS float* scr, int row0, int lane) {
;     ...
;     for (int k0 = 0; k0 < DM; k0 += 32) acc = __builtin_amdgcn_mfma_f32_16x16x32_bf16(*(const bf16x8*)(bp + k0), *(const bf16x8*)(ap + k0), acc, 0, 0, 0);
;     const float rs = pg8::rs_of_row(SS, row0 + fr, fq);
;     *(LAS f32x4*)(scr + fr * 16 + 4 * fq) = acc * rs;
.LBB0_241:
	v_add_u32_e32 v8, s12, v156
	s_load_dwordx4 s[4:7], s[10:11], 0xb8
	s_lshr_b64 s[10:11], s[46:47], 1
	v_ashrrev_i32_e32 v9, 31, v8
	s_lshr_b32 s11, s47, 1
	v_lshlrev_b64 v[4:5], 11, v[8:9]
	s_mul_i32 s11, s11, 0x680000
	s_mul_hi_u32 s13, s10, 0x680000
	v_or_b32_e32 v4, v4, v49
	s_add_i32 s13, s13, s11
	s_mul_i32 s14, s10, 0x680000
	v_lshl_add_u64 v[4:5], s[0:1], 0, v[4:5]
	s_mov_b64 s[10:11], 0xc300100
	v_lshl_add_u64 v[10:11], v[4:5], 0, s[10:11]
	v_lshlrev_b32_e32 v4, 11, v156
	v_or3_b32 v4, s14, v4, v49
	v_mov_b32_e32 v5, s13
	v_lshl_add_u64 v[4:5], s[0:1], 0, v[4:5]
	s_mov_b64 s[10:11], 0x7300100
	v_lshl_add_u64 v[12:13], v[4:5], 0, s[10:11]
	v_mov_b32_e32 v4, 0
	s_movk_i32 s10, 0xffe0
	v_mov_b32_e32 v5, v4
	v_mov_b32_e32 v6, v4
	v_mov_b32_e32 v7, v4
	s_mov_b64 s[14:15], 0x400
.LBB0_242:
	global_load_dwordx4 v[50:53], v[12:13], off offset:-256
	global_load_dwordx4 v[114:117], v[10:11], off offset:-256
	global_load_dwordx4 v[54:57], v[12:13], off offset:-192
	global_load_dwordx4 v[118:121], v[10:11], off offset:-192
	global_load_dwordx4 v[58:61], v[12:13], off offset:-128
	global_load_dwordx4 v[122:125], v[10:11], off offset:-128
	global_load_dwordx4 v[62:65], v[12:13], off offset:-64
	global_load_dwordx4 v[126:129], v[10:11], off offset:-64
	global_load_dwordx4 v[66:69], v[12:13], off
	global_load_dwordx4 v[130:133], v[10:11], off
	global_load_dwordx4 v[70:73], v[12:13], off offset:64
	global_load_dwordx4 v[134:137], v[10:11], off offset:64
	global_load_dwordx4 v[74:77], v[12:13], off offset:128
	global_load_dwordx4 v[138:141], v[10:11], off offset:128
	global_load_dwordx4 v[78:81], v[12:13], off offset:192
	global_load_dwordx4 v[142:145], v[10:11], off offset:192
	global_load_dwordx4 v[82:85], v[12:13], off offset:256
	global_load_dwordx4 v[146:149], v[10:11], off offset:256
	global_load_dwordx4 v[86:89], v[12:13], off offset:320
	global_load_dwordx4 v[150:153], v[10:11], off offset:320
	global_load_dwordx4 v[90:93], v[12:13], off offset:384
	global_load_dwordx4 v[170:173], v[10:11], off offset:384
	global_load_dwordx4 v[94:97], v[12:13], off offset:448
	global_load_dwordx4 v[174:177], v[10:11], off offset:448
	global_load_dwordx4 v[98:101], v[12:13], off offset:512
	global_load_dwordx4 v[178:181], v[10:11], off offset:512
	global_load_dwordx4 v[102:105], v[12:13], off offset:576
	global_load_dwordx4 v[182:185], v[10:11], off offset:576
	global_load_dwordx4 v[106:109], v[12:13], off offset:640
	global_load_dwordx4 v[186:189], v[10:11], off offset:640
	global_load_dwordx4 v[110:113], v[12:13], off offset:704
	global_load_dwordx4 v[190:193], v[10:11], off offset:704
	s_addk_i32 s10, 0x200
	v_lshl_add_u64 v[10:11], v[10:11], 0, s[14:15]
	v_lshl_add_u64 v[12:13], v[12:13], 0, s[14:15]
	s_waitcnt vmcnt(30)
	v_mfma_f32_16x16x32_bf16 v[4:7], v[50:53], v[114:117], v[4:7]
	s_waitcnt vmcnt(28)
	v_mfma_f32_16x16x32_bf16 v[4:7], v[54:57], v[118:121], v[4:7]
	s_waitcnt vmcnt(26)
	v_mfma_f32_16x16x32_bf16 v[4:7], v[58:61], v[122:125], v[4:7]
	s_waitcnt vmcnt(24)
	v_mfma_f32_16x16x32_bf16 v[4:7], v[62:65], v[126:129], v[4:7]
	s_waitcnt vmcnt(22)
	v_mfma_f32_16x16x32_bf16 v[4:7], v[66:69], v[130:133], v[4:7]
	s_waitcnt vmcnt(20)
	v_mfma_f32_16x16x32_bf16 v[4:7], v[70:73], v[134:137], v[4:7]
	s_waitcnt vmcnt(18)
	v_mfma_f32_16x16x32_bf16 v[4:7], v[74:77], v[138:141], v[4:7]
	s_waitcnt vmcnt(16)
	v_mfma_f32_16x16x32_bf16 v[4:7], v[78:81], v[142:145], v[4:7]
	s_waitcnt vmcnt(14)
	v_mfma_f32_16x16x32_bf16 v[4:7], v[82:85], v[146:149], v[4:7]
	s_waitcnt vmcnt(12)
	v_mfma_f32_16x16x32_bf16 v[4:7], v[86:89], v[150:153], v[4:7]
	s_waitcnt vmcnt(10)
	v_mfma_f32_16x16x32_bf16 v[4:7], v[90:93], v[170:173], v[4:7]
	s_waitcnt vmcnt(8)
	v_mfma_f32_16x16x32_bf16 v[4:7], v[94:97], v[174:177], v[4:7]
	s_waitcnt vmcnt(6)
	v_mfma_f32_16x16x32_bf16 v[4:7], v[98:101], v[178:181], v[4:7]
	s_waitcnt vmcnt(4)
	v_mfma_f32_16x16x32_bf16 v[4:7], v[102:105], v[182:185], v[4:7]
	s_waitcnt vmcnt(2)
	v_mfma_f32_16x16x32_bf16 v[4:7], v[106:109], v[186:189], v[4:7]
	s_waitcnt vmcnt(0)
	v_mfma_f32_16x16x32_bf16 v[4:7], v[110:113], v[190:193], v[4:7]
	s_cmpk_gt_u32 s10, 0x3df
	s_cbranch_scc0 .LBB0_242
	v_lshlrev_b64 v[8:9], 7, v[8:9]
	v_lshl_add_u64 v[8:9], s[8:9], 0, v[8:9]
	v_mov_b32_e32 v39, v2
	v_lshl_add_u64 v[12:13], v[8:9], 0, v[38:39]
	global_load_dwordx4 v[8:11], v[12:13], off
	s_nop 0
	global_load_dwordx4 v[12:15], v[12:13], off offset:16
	s_lshl_b64 s[8:9], s[94:95], 15
	s_waitcnt lgkmcnt(0)
	s_add_u32 s4, s4, s8
	s_addc_u32 s5, s5, s9
	s_lshl_b32 s34, s94, 9
	s_lshl_b64 s[8:9], s[34:35], 2
	s_add_u32 s6, s6, s8
	s_addc_u32 s7, s7, s9
	s_lshl_b32 s3, s3, 10
	s_add_i32 s3, s3, 0
	v_add3_u32 v3, s3, v3, v49
	s_ashr_i32 s13, s12, 31
	s_lshl_b64 s[8:9], s[12:13], 11
	s_add_u32 s0, s0, s8
	v_mov_b32_e32 v37, v2
	s_addc_u32 s1, s1, s9
	s_mov_b32 s8, 0
	s_waitcnt vmcnt(1)
	v_add_f32_e32 v8, v8, v9
	v_add_f32_e32 v9, v10, v11
	s_waitcnt vmcnt(0)
	v_add_f32_e32 v10, v12, v13
	v_add_f32_e32 v11, v14, v15
	v_add_f32_e32 v8, v8, v9
	v_add_f32_e32 v9, v10, v11
	v_add_f32_e32 v8, v8, v9
	v_mov_b32_e32 v9, v8
	s_nop 1
	v_permlane16_swap_b32_e32 v8, v9
	v_add_f32_e32 v8, v8, v9
	v_mov_b32_e32 v9, v8
	s_nop 1
	v_permlane32_swap_b32_e32 v8, v9
	v_add_f32_e32 v8, v8, v9
	v_fmamk_f32 v8, v8, 0x3a800000, v1
	v_rsq_f32_e32 v8, v8
	s_nop 0
	v_pk_mul_f32 v[6:7], v[6:7], v[8:9] op_sel_hi:[1,0]
	v_pk_mul_f32 v[4:5], v[4:5], v[8:9] op_sel_hi:[1,0]
	ds_write_b128 v3, v[4:7]
	s_waitcnt lgkmcnt(0)
	v_lshl_add_u64 v[4:5], s[0:1], 0, v[36:37]

; __device__ __forceinline__ void grp_barrier(const XcdBarrier& b, unsigned gsz) {
;     asm volatile("s_waitcnt vmcnt(0)" ::: "memory");
;     __syncthreads();
;     if (threadIdx.x == 0) {
;         unsigned* bar = b.bar;
;         __builtin_amdgcn_s_waitcnt(0);
;         unsigned nloc = b.st[0], nx = b.st[1];
;         if (nloc == 0u) { grp_barrier_complete(bar, b.x, gsz, nloc, nx); b.st[0] = nloc; b.st[1] = nx; }
.LBB0_248:
	s_mov_b64 s[4:5], s[48:49]
	s_mov_b32 s6, s2
	s_getreg_b32 s3, hwreg(HW_REG_XCC_ID, 0, 4)
	s_waitcnt vmcnt(0)
	s_waitcnt vmcnt(0)
	v_readfirstlane_b32 s0, v0
	s_nop 3
	s_cmp_lt_u32 s0, 64
	s_cbranch_scc0 .Lgb_noinv0
	buffer_inv sc1
.Lgb_noinv0:
	s_barrier
	s_mov_b64 s[0:1], exec
	v_readlane_b32 s8, v250, 8
	v_readlane_b32 s9, v250, 9
	s_and_b64 s[8:9], s[0:1], s[8:9]
	s_mov_b64 exec, s[8:9]
	s_cbranch_execz .LBB0_308
	s_load_dwordx2 s[4:5], s[4:5], 0x110
	s_and_b32 s6, s6, 7
	v_readlane_b32 s7, v250, 4
	s_mulk_i32 s6, 0x3600
	s_waitcnt lgkmcnt(0)
	v_mov_b32_e32 v3, s7
	ds_read_b32 v5, v3
	s_add_u32 s6, s4, s6
	v_readlane_b32 s4, v250, 5
	s_addc_u32 s7, s5, 0
	s_and_b32 s3, s3, 15
	v_mov_b32_e32 v3, s4
	ds_read_b32 v4, v3
	s_waitcnt lgkmcnt(1)
	v_cmp_ne_u32_e32 vcc, 0, v5
	s_cbranch_vccnz .LBB0_264
	s_add_u32 s4, s6, 0x7800
	s_addc_u32 s5, s7, 0
	s_add_u32 s8, s6, 0x7a00
	s_addc_u32 s9, s7, 0
	s_add_u32 s10, s6, 0x7b00
	s_addc_u32 s11, s7, 0
	s_add_u32 s12, s6, 0x7c00
	s_addc_u32 s13, s7, 0
	s_add_u32 s14, s6, 0x7d00
	s_addc_u32 s15, s7, 0
	s_add_u32 s16, s6, 0x7e00
	s_addc_u32 s17, s7, 0
	s_add_u32 s18, s6, 0x7f00
	s_addc_u32 s19, s7, 0
	s_add_u32 s20, s6, 0x8000
	s_addc_u32 s21, s7, 0
	s_add_u32 s22, s6, 0x8100
	s_addc_u32 s23, s7, 0
	s_add_u32 s24, s6, 0x8200
	s_addc_u32 s25, s7, 0
	s_add_u32 s28, s6, 0x8300
	s_addc_u32 s29, s7, 0
	s_add_u32 s30, s6, 0x8400
	s_addc_u32 s31, s7, 0
	s_add_u32 s36, s6, 0x8500
	s_addc_u32 s37, s7, 0
	s_add_u32 s38, s6, 0x8600
	s_addc_u32 s39, s7, 0
	s_add_u32 s40, s6, 0x8700
	s_addc_u32 s41, s7, 0
	s_add_u32 s42, s6, 0x8800
	s_addc_u32 s43, s7, 0
	s_add_u32 s54, s6, 0x8900
	s_addc_u32 s55, s7, 0
	s_mov_b32 s27, 1
	s_branch .LBB0_252

; __device__ __forceinline__ unsigned xb_ld(unsigned* p)              { return __hip_atomic_load(p, __ATOMIC_RELAXED, __HIP_MEMORY_SCOPE_AGENT); }
; __device__ __forceinline__ unsigned xb_add(unsigned* p, unsigned v) { return __hip_atomic_fetch_add(p, v, __ATOMIC_RELAXED, __HIP_MEMORY_SCOPE_AGENT); }
; #define XB_SPIN(cond, bar) do { unsigned _sp = 0; while (cond) { __builtin_amdgcn_s_sleep(1); \
;     if ((++_sp & 255u) == 0u) { if (xb_ld(&(bar)[XB_TMO])) break; if (_sp > XB_SPIN_CAP) { atomicAdd(&(bar)[XB_TMO], 1u); break; } } } } while (0)
; __device__ __forceinline__ void grp_barrier(const XcdBarrier& b, unsigned gsz) {
;     ...
;         const unsigned old = xb_add(&bar[XB_XSUB(b.x)], 1u);
;         const bool early = (nx == 1u);
;         if (early) __builtin_amdgcn_fence(__ATOMIC_ACQUIRE, "agent");
;         const unsigned gen = old / nloc;
;         if (old + 1u == (gen + 1u) * nloc) {
;             if (nx > 1u) __builtin_amdgcn_fence(__ATOMIC_RELEASE, "agent");
;             if (!early) asm volatile("s_waitcnt vmcnt(0)" ::: "memory");
;             if (!early) {
;             const unsigned og = xb_add(&bar[XB_TOP], 1u);
;             const unsigned tg = og / nx;
;             if (og + 1u == (tg + 1u) * nx) xb_add(&bar[XB_TOPGEN], 1u);
;             else XB_SPIN(xb_ld(&bar[XB_TOPGEN]) == tg, bar);
;             }
;             if (!early) __builtin_amdgcn_fence(__ATOMIC_ACQUIRE, "agent");
;             xb_add(&bar[XB_XGEN(b.x)], 1u);
;             asm volatile("s_waitcnt vmcnt(0)" ::: "memory");
;         } else {
;             XB_SPIN(xb_ld(&bar[XB_XGEN(b.x)]) == gen, bar);
.LBB0_266:
	s_or_b64 exec, exec, s[10:11]
	s_waitcnt lgkmcnt(0)
	v_cmp_ne_u32_e64 s[4:5], 1, v4
	s_waitcnt vmcnt(0)
	v_readfirstlane_b32 s3, v6
	s_and_b64 vcc, exec, s[4:5]
	s_cbranch_vccnz .LBB0_268
.LBB0_268:
	v_cvt_f32_u32_e32 v6, v5
	v_add_u32_e32 v7, s3, v3
	v_sub_u32_e32 v3, 0, v5
	v_rcp_iflag_f32_e32 v6, v6
	s_nop 0
	v_mul_f32_e32 v6, 0x4f7ffffe, v6
	v_cvt_u32_f32_e32 v6, v6
	v_mul_lo_u32 v3, v3, v6
	v_mul_hi_u32 v3, v6, v3
	v_add_u32_e32 v3, v6, v3
	v_mul_hi_u32 v3, v7, v3
	v_mul_lo_u32 v6, v3, v5
	v_sub_u32_e32 v6, v7, v6
	v_add_u32_e32 v8, 1, v3
	v_cmp_ge_u32_e32 vcc, v6, v5
	s_nop 1
	v_cndmask_b32_e32 v3, v3, v8, vcc
	v_sub_u32_e32 v8, v6, v5
	v_cndmask_b32_e32 v6, v6, v8, vcc
	v_add_u32_e32 v8, 1, v3
	v_cmp_ge_u32_e32 vcc, v6, v5
	v_add_u32_e32 v6, 1, v7
	s_nop 0
	v_cndmask_b32_e32 v3, v3, v8, vcc
	v_mul_lo_u32 v7, v5, v3
	v_add_u32_e32 v5, v7, v5
	v_cmp_ne_u32_e32 vcc, v6, v5
	s_and_saveexec_b64 s[10:11], vcc
	s_xor_b64 s[10:11], exec, s[10:11]
	s_cbranch_execz .LBB0_284
	global_load_dword v4, v203, s[8:9] offset:1024 sc1
	s_add_u32 s16, s8, 0x2400
	s_addc_u32 s17, s9, 0
	s_waitcnt vmcnt(0)
	v_cmp_eq_u32_e32 vcc, v4, v3
	s_and_saveexec_b64 s[12:13], vcc
	s_cbranch_execz .LBB0_281
	s_add_u32 s14, s6, 0x7800
	s_addc_u32 s15, s7, 0
	s_mov_b32 s3, 1
	s_mov_b64 s[18:19], 0
	s_branch .LBB0_272

; __device__ __forceinline__ void grp_barrier(const XcdBarrier& b, unsigned gsz) {
;     asm volatile("s_waitcnt vmcnt(0)" ::: "memory");
;     __syncthreads();
.LBB0_356:
	s_mov_b64 s[4:5], s[48:49]
	s_mov_b32 s6, s2
	s_getreg_b32 s3, hwreg(HW_REG_XCC_ID, 0, 4)
	s_waitcnt vmcnt(0)
	s_waitcnt vmcnt(63) expcnt(7) lgkmcnt(15)
	v_readfirstlane_b32 s0, v0
	s_nop 3
	s_cmp_lt_u32 s0, 64
	s_cbranch_scc0 .Lgb_noinv1
	buffer_inv sc1

; __device__ __forceinline__ unsigned xb_ld(unsigned* p)              { return __hip_atomic_load(p, __ATOMIC_RELAXED, __HIP_MEMORY_SCOPE_AGENT); }
; __device__ __forceinline__ unsigned xb_add(unsigned* p, unsigned v) { return __hip_atomic_fetch_add(p, v, __ATOMIC_RELAXED, __HIP_MEMORY_SCOPE_AGENT); }
; #define XB_SPIN(cond, bar) do { unsigned _sp = 0; while (cond) { __builtin_amdgcn_s_sleep(1); \
;     if ((++_sp & 255u) == 0u) { if (xb_ld(&(bar)[XB_TMO])) break; if (_sp > XB_SPIN_CAP) { atomicAdd(&(bar)[XB_TMO], 1u); break; } } } } while (0)
; __device__ __forceinline__ void grp_barrier(const XcdBarrier& b, unsigned gsz) {
;     ...
;         const unsigned old = xb_add(&bar[XB_XSUB(b.x)], 1u);
;         const bool early = (nx == 1u);
;         if (early) __builtin_amdgcn_fence(__ATOMIC_ACQUIRE, "agent");
;         const unsigned gen = old / nloc;
;         if (old + 1u == (gen + 1u) * nloc) {
;             if (nx > 1u) __builtin_amdgcn_fence(__ATOMIC_RELEASE, "agent");
;             if (!early) asm volatile("s_waitcnt vmcnt(0)" ::: "memory");
;             if (!early) {
;             const unsigned og = xb_add(&bar[XB_TOP], 1u);
;             const unsigned tg = og / nx;
;             if (og + 1u == (tg + 1u) * nx) xb_add(&bar[XB_TOPGEN], 1u);
;             else XB_SPIN(xb_ld(&bar[XB_TOPGEN]) == tg, bar);
;             }
;             if (!early) __builtin_amdgcn_fence(__ATOMIC_ACQUIRE, "agent");
;             xb_add(&bar[XB_XGEN(b.x)], 1u);
;             asm volatile("s_waitcnt vmcnt(0)" ::: "memory");
;         } else {
;             XB_SPIN(xb_ld(&bar[XB_XGEN(b.x)]) == gen, bar);
.LBB0_374:
	s_or_b64 exec, exec, s[10:11]
	s_waitcnt lgkmcnt(0)
	v_cmp_ne_u32_e64 s[4:5], 1, v4
	s_waitcnt vmcnt(0)
	v_readfirstlane_b32 s3, v6
	s_and_b64 vcc, exec, s[4:5]
	s_cbranch_vccnz .LBB0_376
.LBB0_376:
	v_cvt_f32_u32_e32 v6, v5
	v_add_u32_e32 v7, s3, v3
	v_sub_u32_e32 v3, 0, v5
	v_rcp_iflag_f32_e32 v6, v6
	s_nop 0
	v_mul_f32_e32 v6, 0x4f7ffffe, v6
	v_cvt_u32_f32_e32 v6, v6
	v_mul_lo_u32 v3, v3, v6
	v_mul_hi_u32 v3, v6, v3
	v_add_u32_e32 v3, v6, v3
	v_mul_hi_u32 v3, v7, v3
	v_mul_lo_u32 v6, v3, v5
	v_sub_u32_e32 v6, v7, v6
	v_add_u32_e32 v8, 1, v3
	v_cmp_ge_u32_e32 vcc, v6, v5
	s_nop 1
	v_cndmask_b32_e32 v3, v3, v8, vcc
	v_sub_u32_e32 v8, v6, v5
	v_cndmask_b32_e32 v6, v6, v8, vcc
	v_add_u32_e32 v8, 1, v3
	v_cmp_ge_u32_e32 vcc, v6, v5
	v_add_u32_e32 v6, 1, v7
	s_nop 0
	v_cndmask_b32_e32 v3, v3, v8, vcc
	v_mul_lo_u32 v7, v5, v3
	v_add_u32_e32 v5, v7, v5
	v_cmp_ne_u32_e32 vcc, v6, v5
	s_and_saveexec_b64 s[10:11], vcc
	s_xor_b64 s[10:11], exec, s[10:11]
	s_cbranch_execz .LBB0_392
	global_load_dword v4, v203, s[8:9] offset:1024 sc1
	s_add_u32 s16, s8, 0x2400
	s_addc_u32 s17, s9, 0
	s_waitcnt vmcnt(0)
	v_cmp_eq_u32_e32 vcc, v4, v3
	s_and_saveexec_b64 s[12:13], vcc
	s_cbranch_execz .LBB0_389
	s_add_u32 s14, s6, 0x7800
	s_addc_u32 s15, s7, 0
	s_mov_b32 s3, 1
	s_mov_b64 s[18:19], 0
	s_branch .LBB0_380

; __device__ __forceinline__ void grp_barrier(const XcdBarrier& b, unsigned gsz) {
;     asm volatile("s_waitcnt vmcnt(0)" ::: "memory");
;     __syncthreads();
.LBB0_421:
	s_or_b64 exec, exec, s[0:1]
	s_mov_b64 s[4:5], s[48:49]
	s_mov_b32 s6, s2
	s_getreg_b32 s3, hwreg(HW_REG_XCC_ID, 0, 4)
	s_waitcnt vmcnt(0)
	v_readfirstlane_b32 s0, v0
	s_nop 3
	s_cmp_lt_u32 s0, 64
	s_cbranch_scc0 .Lgb_noinv2
	buffer_inv sc1

; __device__ __forceinline__ unsigned xb_ld(unsigned* p)              { return __hip_atomic_load(p, __ATOMIC_RELAXED, __HIP_MEMORY_SCOPE_AGENT); }
; __device__ __forceinline__ unsigned xb_add(unsigned* p, unsigned v) { return __hip_atomic_fetch_add(p, v, __ATOMIC_RELAXED, __HIP_MEMORY_SCOPE_AGENT); }
; #define XB_SPIN(cond, bar) do { unsigned _sp = 0; while (cond) { __builtin_amdgcn_s_sleep(1); \
;     if ((++_sp & 255u) == 0u) { if (xb_ld(&(bar)[XB_TMO])) break; if (_sp > XB_SPIN_CAP) { atomicAdd(&(bar)[XB_TMO], 1u); break; } } } } while (0)
; __device__ __forceinline__ void grp_barrier(const XcdBarrier& b, unsigned gsz) {
;     ...
;         const unsigned old = xb_add(&bar[XB_XSUB(b.x)], 1u);
;         const bool early = (nx == 1u);
;         if (early) __builtin_amdgcn_fence(__ATOMIC_ACQUIRE, "agent");
;         const unsigned gen = old / nloc;
;         if (old + 1u == (gen + 1u) * nloc) {
;             if (nx > 1u) __builtin_amdgcn_fence(__ATOMIC_RELEASE, "agent");
;             if (!early) asm volatile("s_waitcnt vmcnt(0)" ::: "memory");
;             if (!early) {
;             const unsigned og = xb_add(&bar[XB_TOP], 1u);
;             const unsigned tg = og / nx;
;             if (og + 1u == (tg + 1u) * nx) xb_add(&bar[XB_TOPGEN], 1u);
;             else XB_SPIN(xb_ld(&bar[XB_TOPGEN]) == tg, bar);
;             }
;             if (!early) __builtin_amdgcn_fence(__ATOMIC_ACQUIRE, "agent");
;             xb_add(&bar[XB_XGEN(b.x)], 1u);
;             asm volatile("s_waitcnt vmcnt(0)" ::: "memory");
;         } else {
;             XB_SPIN(xb_ld(&bar[XB_XGEN(b.x)]) == gen, bar);
.LBB0_439:
	s_or_b64 exec, exec, s[10:11]
	s_waitcnt lgkmcnt(0)
	v_cmp_ne_u32_e64 s[4:5], 1, v4
	s_waitcnt vmcnt(0)
	v_readfirstlane_b32 s3, v6
	s_and_b64 vcc, exec, s[4:5]
	s_cbranch_vccnz .LBB0_441
.LBB0_441:
	v_cvt_f32_u32_e32 v6, v5
	v_add_u32_e32 v7, s3, v3
	v_sub_u32_e32 v3, 0, v5
	v_rcp_iflag_f32_e32 v6, v6
	s_nop 0
	v_mul_f32_e32 v6, 0x4f7ffffe, v6
	v_cvt_u32_f32_e32 v6, v6
	v_mul_lo_u32 v3, v3, v6
	v_mul_hi_u32 v3, v6, v3
	v_add_u32_e32 v3, v6, v3
	v_mul_hi_u32 v3, v7, v3
	v_mul_lo_u32 v6, v3, v5
	v_sub_u32_e32 v6, v7, v6
	v_add_u32_e32 v8, 1, v3
	v_cmp_ge_u32_e32 vcc, v6, v5
	s_nop 1
	v_cndmask_b32_e32 v3, v3, v8, vcc
	v_sub_u32_e32 v8, v6, v5
	v_cndmask_b32_e32 v6, v6, v8, vcc
	v_add_u32_e32 v8, 1, v3
	v_cmp_ge_u32_e32 vcc, v6, v5
	v_add_u32_e32 v6, 1, v7
	s_nop 0
	v_cndmask_b32_e32 v3, v3, v8, vcc
	v_mul_lo_u32 v7, v5, v3
	v_add_u32_e32 v5, v7, v5
	v_cmp_ne_u32_e32 vcc, v6, v5
	s_and_saveexec_b64 s[10:11], vcc
	s_xor_b64 s[10:11], exec, s[10:11]
	s_cbranch_execz .LBB0_457
	global_load_dword v4, v203, s[8:9] offset:1024 sc1
	s_add_u32 s16, s8, 0x2400
	s_addc_u32 s17, s9, 0
	s_waitcnt vmcnt(0)
	v_cmp_eq_u32_e32 vcc, v4, v3
	s_and_saveexec_b64 s[12:13], vcc
	s_cbranch_execz .LBB0_454
	s_add_u32 s14, s6, 0x7800
	s_addc_u32 s15, s7, 0
	s_mov_b32 s3, 1
	s_mov_b64 s[18:19], 0
	s_branch .LBB0_445

; __device__ __forceinline__ void grp_barrier(const XcdBarrier& b, unsigned gsz) {
;     asm volatile("s_waitcnt vmcnt(0)" ::: "memory");
;     __syncthreads();
.LBB0_541:
	s_mov_b32 s6, s2
	s_mov_b64 s[4:5], s[48:49]
	s_getreg_b32 s3, hwreg(HW_REG_XCC_ID, 0, 4)
	s_waitcnt vmcnt(0)
	s_waitcnt vmcnt(63) expcnt(7) lgkmcnt(15)
	v_readfirstlane_b32 s0, v0
	s_nop 3
	s_cmp_lt_u32 s0, 64
	s_cbranch_scc0 .Lgb_noinv3
	buffer_inv sc1

; __device__ __forceinline__ unsigned xb_ld(unsigned* p)              { return __hip_atomic_load(p, __ATOMIC_RELAXED, __HIP_MEMORY_SCOPE_AGENT); }
; __device__ __forceinline__ unsigned xb_add(unsigned* p, unsigned v) { return __hip_atomic_fetch_add(p, v, __ATOMIC_RELAXED, __HIP_MEMORY_SCOPE_AGENT); }
; #define XB_SPIN(cond, bar) do { unsigned _sp = 0; while (cond) { __builtin_amdgcn_s_sleep(1); \
;     if ((++_sp & 255u) == 0u) { if (xb_ld(&(bar)[XB_TMO])) break; if (_sp > XB_SPIN_CAP) { atomicAdd(&(bar)[XB_TMO], 1u); break; } } } } while (0)
; __device__ __forceinline__ void grp_barrier(const XcdBarrier& b, unsigned gsz) {
;     ...
;         const unsigned old = xb_add(&bar[XB_XSUB(b.x)], 1u);
;         const bool early = (nx == 1u);
;         if (early) __builtin_amdgcn_fence(__ATOMIC_ACQUIRE, "agent");
;         const unsigned gen = old / nloc;
;         if (old + 1u == (gen + 1u) * nloc) {
;             if (nx > 1u) __builtin_amdgcn_fence(__ATOMIC_RELEASE, "agent");
;             if (!early) asm volatile("s_waitcnt vmcnt(0)" ::: "memory");
;             if (!early) {
;             const unsigned og = xb_add(&bar[XB_TOP], 1u);
;             const unsigned tg = og / nx;
;             if (og + 1u == (tg + 1u) * nx) xb_add(&bar[XB_TOPGEN], 1u);
;             else XB_SPIN(xb_ld(&bar[XB_TOPGEN]) == tg, bar);
;             }
;             if (!early) __builtin_amdgcn_fence(__ATOMIC_ACQUIRE, "agent");
;             xb_add(&bar[XB_XGEN(b.x)], 1u);
;             asm volatile("s_waitcnt vmcnt(0)" ::: "memory");
;         } else {
;             XB_SPIN(xb_ld(&bar[XB_XGEN(b.x)]) == gen, bar);
.LBB0_559:
	s_or_b64 exec, exec, s[10:11]
	s_waitcnt lgkmcnt(0)
	v_cmp_ne_u32_e64 s[4:5], 1, v4
	s_waitcnt vmcnt(0)
	v_readfirstlane_b32 s3, v6
	s_and_b64 vcc, exec, s[4:5]
	s_cbranch_vccnz .LBB0_561
.LBB0_561:
	v_cvt_f32_u32_e32 v6, v5
	v_add_u32_e32 v7, s3, v3
	v_sub_u32_e32 v3, 0, v5
	v_rcp_iflag_f32_e32 v6, v6
	s_nop 0
	v_mul_f32_e32 v6, 0x4f7ffffe, v6
	v_cvt_u32_f32_e32 v6, v6
	v_mul_lo_u32 v3, v3, v6
	v_mul_hi_u32 v3, v6, v3
	v_add_u32_e32 v3, v6, v3
	v_mul_hi_u32 v3, v7, v3
	v_mul_lo_u32 v6, v3, v5
	v_sub_u32_e32 v6, v7, v6
	v_add_u32_e32 v8, 1, v3
	v_cmp_ge_u32_e32 vcc, v6, v5
	s_nop 1
	v_cndmask_b32_e32 v3, v3, v8, vcc
	v_sub_u32_e32 v8, v6, v5
	v_cndmask_b32_e32 v6, v6, v8, vcc
	v_add_u32_e32 v8, 1, v3
	v_cmp_ge_u32_e32 vcc, v6, v5
	v_add_u32_e32 v6, 1, v7
	s_nop 0
	v_cndmask_b32_e32 v3, v3, v8, vcc
	v_mul_lo_u32 v7, v5, v3
	v_add_u32_e32 v5, v7, v5
	v_cmp_ne_u32_e32 vcc, v6, v5
	s_and_saveexec_b64 s[10:11], vcc
	s_xor_b64 s[10:11], exec, s[10:11]
	s_cbranch_execz .LBB0_577
	global_load_dword v4, v203, s[8:9] offset:1024 sc1
	s_add_u32 s16, s8, 0x2400
	s_addc_u32 s17, s9, 0
	s_waitcnt vmcnt(0)
	v_cmp_eq_u32_e32 vcc, v4, v3
	s_and_saveexec_b64 s[12:13], vcc
	s_cbranch_execz .LBB0_574
	s_add_u32 s14, s6, 0x7800
	s_addc_u32 s15, s7, 0
	s_mov_b32 s3, 1
	s_mov_b64 s[18:19], 0
	s_branch .LBB0_565

; __device__ __forceinline__ void grp_barrier(const XcdBarrier& b, unsigned gsz) {
;     asm volatile("s_waitcnt vmcnt(0)" ::: "memory");
;     __syncthreads();
.LBB0_751:
	s_or_b64 exec, exec, s[4:5]
	v_lshlrev_b64 v[4:5], 11, v[24:25]
	v_lshl_add_u64 v[4:5], v[16:17], 0, v[4:5]
	v_lshl_add_u64 v[4:5], v[30:31], 1, v[4:5]
	s_mov_b32 s6, s2
	s_mov_b64 s[4:5], s[48:49]
	global_store_dwordx4 v[4:5], v[8:11], off
	s_getreg_b32 s3, hwreg(HW_REG_XCC_ID, 0, 4)
	s_waitcnt vmcnt(0)
	s_waitcnt vmcnt(0)
	v_readfirstlane_b32 s0, v0
	s_nop 3
	s_cmp_lt_u32 s0, 64
	s_cbranch_scc0 .Lgb_noinv4
	buffer_inv sc1

; __device__ __forceinline__ unsigned xb_ld(unsigned* p)              { return __hip_atomic_load(p, __ATOMIC_RELAXED, __HIP_MEMORY_SCOPE_AGENT); }
; __device__ __forceinline__ unsigned xb_add(unsigned* p, unsigned v) { return __hip_atomic_fetch_add(p, v, __ATOMIC_RELAXED, __HIP_MEMORY_SCOPE_AGENT); }
; #define XB_SPIN(cond, bar) do { unsigned _sp = 0; while (cond) { __builtin_amdgcn_s_sleep(1); \
;     if ((++_sp & 255u) == 0u) { if (xb_ld(&(bar)[XB_TMO])) break; if (_sp > XB_SPIN_CAP) { atomicAdd(&(bar)[XB_TMO], 1u); break; } } } } while (0)
; __device__ __forceinline__ void grp_barrier(const XcdBarrier& b, unsigned gsz) {
;     ...
;         const unsigned old = xb_add(&bar[XB_XSUB(b.x)], 1u);
;         const bool early = (nx == 1u);
;         if (early) __builtin_amdgcn_fence(__ATOMIC_ACQUIRE, "agent");
;         const unsigned gen = old / nloc;
;         if (old + 1u == (gen + 1u) * nloc) {
;             if (nx > 1u) __builtin_amdgcn_fence(__ATOMIC_RELEASE, "agent");
;             if (!early) asm volatile("s_waitcnt vmcnt(0)" ::: "memory");
;             if (!early) {
;             const unsigned og = xb_add(&bar[XB_TOP], 1u);
;             const unsigned tg = og / nx;
;             if (og + 1u == (tg + 1u) * nx) xb_add(&bar[XB_TOPGEN], 1u);
;             else XB_SPIN(xb_ld(&bar[XB_TOPGEN]) == tg, bar);
;             }
;             if (!early) __builtin_amdgcn_fence(__ATOMIC_ACQUIRE, "agent");
;             xb_add(&bar[XB_XGEN(b.x)], 1u);
;             asm volatile("s_waitcnt vmcnt(0)" ::: "memory");
;         } else {
;             XB_SPIN(xb_ld(&bar[XB_XGEN(b.x)]) == gen, bar);
.LBB0_771:
	s_or_b64 exec, exec, s[10:11]
	s_waitcnt lgkmcnt(0)
	v_cmp_ne_u32_e64 s[4:5], 1, v4
	s_waitcnt vmcnt(0)
	v_readfirstlane_b32 s3, v6
	s_and_b64 vcc, exec, s[4:5]
	s_cbranch_vccnz .LBB0_773
.LBB0_773:
	v_cvt_f32_u32_e32 v6, v5
	v_add_u32_e32 v7, s3, v3
	v_sub_u32_e32 v3, 0, v5
	v_rcp_iflag_f32_e32 v6, v6
	s_nop 0
	v_mul_f32_e32 v6, 0x4f7ffffe, v6
	v_cvt_u32_f32_e32 v6, v6
	v_mul_lo_u32 v3, v3, v6
	v_mul_hi_u32 v3, v6, v3
	v_add_u32_e32 v3, v6, v3
	v_mul_hi_u32 v3, v7, v3
	v_mul_lo_u32 v6, v3, v5
	v_sub_u32_e32 v6, v7, v6
	v_add_u32_e32 v8, 1, v3
	v_cmp_ge_u32_e32 vcc, v6, v5
	s_nop 1
	v_cndmask_b32_e32 v3, v3, v8, vcc
	v_sub_u32_e32 v8, v6, v5
	v_cndmask_b32_e32 v6, v6, v8, vcc
	v_add_u32_e32 v8, 1, v3
	v_cmp_ge_u32_e32 vcc, v6, v5
	v_add_u32_e32 v6, 1, v7
	s_nop 0
	v_cndmask_b32_e32 v3, v3, v8, vcc
	v_mul_lo_u32 v7, v5, v3
	v_add_u32_e32 v5, v7, v5
	v_cmp_ne_u32_e32 vcc, v6, v5
	s_and_saveexec_b64 s[10:11], vcc
	s_xor_b64 s[10:11], exec, s[10:11]
	s_cbranch_execz .LBB0_789
	global_load_dword v4, v203, s[8:9] offset:1024 sc1
	s_add_u32 s16, s8, 0x2400
	s_addc_u32 s17, s9, 0
	s_waitcnt vmcnt(0)
	v_cmp_eq_u32_e32 vcc, v4, v3
	s_and_saveexec_b64 s[12:13], vcc
	s_cbranch_execz .LBB0_786
	s_add_u32 s14, s6, 0x7800
	s_addc_u32 s15, s7, 0
	s_mov_b32 s3, 1
	s_mov_b64 s[18:19], 0
	s_branch .LBB0_777

; __device__ __forceinline__ void grp_barrier(const XcdBarrier& b, unsigned gsz) {
;     asm volatile("s_waitcnt vmcnt(0)" ::: "memory");
;     __syncthreads();
.LBB0_892:
	s_mov_b64 s[4:5], s[48:49]
	s_mov_b32 s6, s2
	s_getreg_b32 s3, hwreg(HW_REG_XCC_ID, 0, 4)
	s_waitcnt vmcnt(0)
	v_readfirstlane_b32 s0, v0
	s_nop 3
	s_cmp_lt_u32 s0, 64
	s_cbranch_scc0 .Lgb_noinv5
	buffer_inv sc1

; __device__ __forceinline__ unsigned xb_ld(unsigned* p)              { return __hip_atomic_load(p, __ATOMIC_RELAXED, __HIP_MEMORY_SCOPE_AGENT); }
; __device__ __forceinline__ unsigned xb_add(unsigned* p, unsigned v) { return __hip_atomic_fetch_add(p, v, __ATOMIC_RELAXED, __HIP_MEMORY_SCOPE_AGENT); }
; #define XB_SPIN(cond, bar) do { unsigned _sp = 0; while (cond) { __builtin_amdgcn_s_sleep(1); \
;     if ((++_sp & 255u) == 0u) { if (xb_ld(&(bar)[XB_TMO])) break; if (_sp > XB_SPIN_CAP) { atomicAdd(&(bar)[XB_TMO], 1u); break; } } } } while (0)
; __device__ __forceinline__ void grp_barrier(const XcdBarrier& b, unsigned gsz) {
;     ...
;         const unsigned old = xb_add(&bar[XB_XSUB(b.x)], 1u);
;         const bool early = (nx == 1u);
;         if (early) __builtin_amdgcn_fence(__ATOMIC_ACQUIRE, "agent");
;         const unsigned gen = old / nloc;
;         if (old + 1u == (gen + 1u) * nloc) {
;             if (nx > 1u) __builtin_amdgcn_fence(__ATOMIC_RELEASE, "agent");
;             if (!early) asm volatile("s_waitcnt vmcnt(0)" ::: "memory");
;             if (!early) {
;             const unsigned og = xb_add(&bar[XB_TOP], 1u);
;             const unsigned tg = og / nx;
;             if (og + 1u == (tg + 1u) * nx) xb_add(&bar[XB_TOPGEN], 1u);
;             else XB_SPIN(xb_ld(&bar[XB_TOPGEN]) == tg, bar);
;             }
;             if (!early) __builtin_amdgcn_fence(__ATOMIC_ACQUIRE, "agent");
;             xb_add(&bar[XB_XGEN(b.x)], 1u);
;             asm volatile("s_waitcnt vmcnt(0)" ::: "memory");
;         } else {
;             XB_SPIN(xb_ld(&bar[XB_XGEN(b.x)]) == gen, bar);
.LBB0_910:
	s_or_b64 exec, exec, s[10:11]
	s_waitcnt lgkmcnt(0)
	v_cmp_ne_u32_e64 s[4:5], 1, v4
	s_waitcnt vmcnt(0)
	v_readfirstlane_b32 s3, v6
	s_and_b64 vcc, exec, s[4:5]
	s_cbranch_vccnz .LBB0_912
.LBB0_912:
	v_cvt_f32_u32_e32 v6, v5
	v_add_u32_e32 v7, s3, v3
	v_sub_u32_e32 v3, 0, v5
	v_rcp_iflag_f32_e32 v6, v6
	s_nop 0
	v_mul_f32_e32 v6, 0x4f7ffffe, v6
	v_cvt_u32_f32_e32 v6, v6
	v_mul_lo_u32 v3, v3, v6
	v_mul_hi_u32 v3, v6, v3
	v_add_u32_e32 v3, v6, v3
	v_mul_hi_u32 v3, v7, v3
	v_mul_lo_u32 v6, v3, v5
	v_sub_u32_e32 v6, v7, v6
	v_add_u32_e32 v8, 1, v3
	v_cmp_ge_u32_e32 vcc, v6, v5
	s_nop 1
	v_cndmask_b32_e32 v3, v3, v8, vcc
	v_sub_u32_e32 v8, v6, v5
	v_cndmask_b32_e32 v6, v6, v8, vcc
	v_add_u32_e32 v8, 1, v3
	v_cmp_ge_u32_e32 vcc, v6, v5
	v_add_u32_e32 v6, 1, v7
	s_nop 0
	v_cndmask_b32_e32 v3, v3, v8, vcc
	v_mul_lo_u32 v7, v5, v3
	v_add_u32_e32 v5, v7, v5
	v_cmp_ne_u32_e32 vcc, v6, v5
	s_and_saveexec_b64 s[10:11], vcc
	s_xor_b64 s[10:11], exec, s[10:11]
	s_cbranch_execz .LBB0_928
	global_load_dword v4, v203, s[8:9] offset:1024 sc1
	s_add_u32 s16, s8, 0x2400
	s_addc_u32 s17, s9, 0
	s_waitcnt vmcnt(0)
	v_cmp_eq_u32_e32 vcc, v4, v3
	s_and_saveexec_b64 s[12:13], vcc
	s_cbranch_execz .LBB0_925
	s_add_u32 s14, s6, 0x7800
	s_addc_u32 s15, s7, 0
	s_mov_b32 s3, 1
	s_mov_b64 s[18:19], 0
	s_branch .LBB0_916

; __device__ __forceinline__ void grp_barrier(const XcdBarrier& b, unsigned gsz) {
;     asm volatile("s_waitcnt vmcnt(0)" ::: "memory");
;     __syncthreads();
;     if (threadIdx.x == 0) {
;         unsigned* bar = b.bar;
;         __builtin_amdgcn_s_waitcnt(0);
;         unsigned nloc = b.st[0], nx = b.st[1];
;         if (nloc == 0u) { grp_barrier_complete(bar, b.x, gsz, nloc, nx); b.st[0] = nloc; b.st[1] = nx; }
.LBB0_1022:
	s_or_b64 exec, exec, s[4:5]
	s_mov_b64 s[4:5], s[48:49]
	s_mov_b32 s6, s2
	s_getreg_b32 s3, hwreg(HW_REG_XCC_ID, 0, 4)
	s_waitcnt vmcnt(0)
	v_readfirstlane_b32 s0, v0
	s_nop 3
	s_cmp_lt_u32 s0, 64
	s_cbranch_scc0 .Lgb_noinv6
	buffer_inv sc1
.Lgb_noinv6:
	s_barrier
	s_and_saveexec_b64 s[0:1], s[88:89]
	s_cbranch_execz .LBB0_1082
	s_load_dwordx2 s[4:5], s[4:5], 0x110
	s_and_b32 s6, s6, 7
	v_readlane_b32 s7, v250, 4
	s_mulk_i32 s6, 0x3600
	s_waitcnt lgkmcnt(0)
	v_mov_b32_e32 v3, s7
	ds_read_b32 v5, v3
	s_add_u32 s6, s4, s6
	v_readlane_b32 s4, v250, 5
	s_addc_u32 s7, s5, 0
	s_and_b32 s3, s3, 15
	v_mov_b32_e32 v3, s4
	ds_read_b32 v4, v3
	s_waitcnt lgkmcnt(1)
	v_cmp_ne_u32_e32 vcc, 0, v5
	s_cbranch_vccnz .LBB0_1038
	s_add_u32 s4, s6, 0x7800
	s_addc_u32 s5, s7, 0
	s_add_u32 s8, s6, 0x7a00
	s_addc_u32 s9, s7, 0
	s_add_u32 s10, s6, 0x7b00
	s_addc_u32 s11, s7, 0
	s_add_u32 s12, s6, 0x7c00
	s_addc_u32 s13, s7, 0
	s_add_u32 s14, s6, 0x7d00
	s_addc_u32 s15, s7, 0
	s_add_u32 s16, s6, 0x7e00
	s_addc_u32 s17, s7, 0
	s_add_u32 s18, s6, 0x7f00
	s_addc_u32 s19, s7, 0
	s_add_u32 s20, s6, 0x8000
	s_addc_u32 s21, s7, 0
	s_add_u32 s22, s6, 0x8100
	s_addc_u32 s23, s7, 0
	s_add_u32 s24, s6, 0x8200
	s_addc_u32 s25, s7, 0
	s_add_u32 s28, s6, 0x8300
	s_addc_u32 s29, s7, 0
	s_add_u32 s30, s6, 0x8400
	s_addc_u32 s31, s7, 0
	s_add_u32 s36, s6, 0x8500
	s_addc_u32 s37, s7, 0
	s_add_u32 s38, s6, 0x8600
	s_addc_u32 s39, s7, 0
	s_add_u32 s40, s6, 0x8700
	s_addc_u32 s41, s7, 0
	s_add_u32 s42, s6, 0x8800
	s_addc_u32 s43, s7, 0
	s_add_u32 s54, s6, 0x8900
	s_addc_u32 s55, s7, 0
	s_mov_b32 s27, 1
	s_branch .LBB0_1026

; __device__ __forceinline__ unsigned xb_ld(unsigned* p)              { return __hip_atomic_load(p, __ATOMIC_RELAXED, __HIP_MEMORY_SCOPE_AGENT); }
; __device__ __forceinline__ unsigned xb_add(unsigned* p, unsigned v) { return __hip_atomic_fetch_add(p, v, __ATOMIC_RELAXED, __HIP_MEMORY_SCOPE_AGENT); }
; #define XB_SPIN(cond, bar) do { unsigned _sp = 0; while (cond) { __builtin_amdgcn_s_sleep(1); \
;     if ((++_sp & 255u) == 0u) { if (xb_ld(&(bar)[XB_TMO])) break; if (_sp > XB_SPIN_CAP) { atomicAdd(&(bar)[XB_TMO], 1u); break; } } } } while (0)
; __device__ __forceinline__ void grp_barrier(const XcdBarrier& b, unsigned gsz) {
;     ...
;         const unsigned old = xb_add(&bar[XB_XSUB(b.x)], 1u);
;         const bool early = (nx == 1u);
;         if (early) __builtin_amdgcn_fence(__ATOMIC_ACQUIRE, "agent");
;         const unsigned gen = old / nloc;
;         if (old + 1u == (gen + 1u) * nloc) {
;             if (nx > 1u) __builtin_amdgcn_fence(__ATOMIC_RELEASE, "agent");
;             if (!early) asm volatile("s_waitcnt vmcnt(0)" ::: "memory");
;             if (!early) {
;             const unsigned og = xb_add(&bar[XB_TOP], 1u);
;             const unsigned tg = og / nx;
;             if (og + 1u == (tg + 1u) * nx) xb_add(&bar[XB_TOPGEN], 1u);
;             else XB_SPIN(xb_ld(&bar[XB_TOPGEN]) == tg, bar);
;             }
;             if (!early) __builtin_amdgcn_fence(__ATOMIC_ACQUIRE, "agent");
;             xb_add(&bar[XB_XGEN(b.x)], 1u);
;             asm volatile("s_waitcnt vmcnt(0)" ::: "memory");
;         } else {
;             XB_SPIN(xb_ld(&bar[XB_XGEN(b.x)]) == gen, bar);
.LBB0_1040:
	s_or_b64 exec, exec, s[10:11]
	s_waitcnt lgkmcnt(0)
	v_cmp_ne_u32_e64 s[4:5], 1, v4
	s_waitcnt vmcnt(0)
	v_readfirstlane_b32 s3, v6
	s_and_b64 vcc, exec, s[4:5]
	s_cbranch_vccnz .LBB0_1042
.LBB0_1042:
	v_cvt_f32_u32_e32 v6, v5
	v_add_u32_e32 v7, s3, v3
	v_sub_u32_e32 v3, 0, v5
	v_rcp_iflag_f32_e32 v6, v6
	s_nop 0
	v_mul_f32_e32 v6, 0x4f7ffffe, v6
	v_cvt_u32_f32_e32 v6, v6
	v_mul_lo_u32 v3, v3, v6
	v_mul_hi_u32 v3, v6, v3
	v_add_u32_e32 v3, v6, v3
	v_mul_hi_u32 v3, v7, v3
	v_mul_lo_u32 v6, v3, v5
	v_sub_u32_e32 v6, v7, v6
	v_add_u32_e32 v8, 1, v3
	v_cmp_ge_u32_e32 vcc, v6, v5
	s_nop 1
	v_cndmask_b32_e32 v3, v3, v8, vcc
	v_sub_u32_e32 v8, v6, v5
	v_cndmask_b32_e32 v6, v6, v8, vcc
	v_add_u32_e32 v8, 1, v3
	v_cmp_ge_u32_e32 vcc, v6, v5
	v_add_u32_e32 v6, 1, v7
	s_nop 0
	v_cndmask_b32_e32 v3, v3, v8, vcc
	v_mul_lo_u32 v7, v5, v3
	v_add_u32_e32 v5, v7, v5
	v_cmp_ne_u32_e32 vcc, v6, v5
	s_and_saveexec_b64 s[10:11], vcc
	s_xor_b64 s[10:11], exec, s[10:11]
	s_cbranch_execz .LBB0_1058
	global_load_dword v4, v203, s[8:9] offset:1024 sc1
	s_add_u32 s16, s8, 0x2400
	s_addc_u32 s17, s9, 0
	s_waitcnt vmcnt(0)
	v_cmp_eq_u32_e32 vcc, v4, v3
	s_and_saveexec_b64 s[12:13], vcc
	s_cbranch_execz .LBB0_1055
	s_add_u32 s14, s6, 0x7800
	s_addc_u32 s15, s7, 0
	s_mov_b32 s3, 1
	s_mov_b64 s[18:19], 0
	s_branch .LBB0_1046

; __device__ __forceinline__ void grp_barrier(const XcdBarrier& b, unsigned gsz) {
;     asm volatile("s_waitcnt vmcnt(0)" ::: "memory");
;     __syncthreads();
;     if (threadIdx.x == 0) {
;         unsigned* bar = b.bar;
;         __builtin_amdgcn_s_waitcnt(0);
;         unsigned nloc = b.st[0], nx = b.st[1];
;         if (nloc == 0u) { grp_barrier_complete(bar, b.x, gsz, nloc, nx); b.st[0] = nloc; b.st[1] = nx; }
.LBB0_1119:
	s_mov_b64 s[4:5], s[48:49]
	s_mov_b32 s10, s2
	s_getreg_b32 s3, hwreg(HW_REG_XCC_ID, 0, 4)
	s_waitcnt vmcnt(0)
	s_waitcnt lgkmcnt(0)
	v_readfirstlane_b32 s0, v0
	s_nop 3
	s_cmp_lt_u32 s0, 64
	s_cbranch_scc0 .Lgb_noinv7
	buffer_inv sc1
.Lgb_noinv7:
	s_barrier
	s_and_saveexec_b64 s[0:1], s[88:89]
	s_cbranch_execz .LBB0_1179
	s_load_dwordx2 s[4:5], s[4:5], 0x110
	s_and_b32 s10, s10, 7
	v_readlane_b32 s11, v250, 4
	s_mulk_i32 s10, 0x3600
	s_waitcnt lgkmcnt(0)
	v_mov_b32_e32 v3, s11
	ds_read_b32 v5, v3
	s_add_u32 s10, s4, s10
	v_readlane_b32 s4, v250, 5
	s_addc_u32 s11, s5, 0
	s_and_b32 s3, s3, 15
	v_mov_b32_e32 v3, s4
	ds_read_b32 v4, v3
	s_waitcnt lgkmcnt(1)
	v_cmp_ne_u32_e32 vcc, 0, v5
	s_cbranch_vccnz .LBB0_1135
	s_add_u32 s4, s10, 0x7800
	s_addc_u32 s5, s11, 0
	s_add_u32 s12, s10, 0x7a00
	s_addc_u32 s13, s11, 0
	s_add_u32 s16, s10, 0x7b00
	s_addc_u32 s17, s11, 0
	s_add_u32 s18, s10, 0x7c00
	s_addc_u32 s19, s11, 0
	s_add_u32 s20, s10, 0x7d00
	s_addc_u32 s21, s11, 0
	s_add_u32 s22, s10, 0x7e00
	s_addc_u32 s23, s11, 0
	s_add_u32 s24, s10, 0x7f00
	s_addc_u32 s25, s11, 0
	s_add_u32 s28, s10, 0x8000
	s_addc_u32 s29, s11, 0
	s_add_u32 s30, s10, 0x8100
	s_addc_u32 s31, s11, 0
	s_add_u32 s36, s10, 0x8200
	s_addc_u32 s37, s11, 0
	s_add_u32 s38, s10, 0x8300
	s_addc_u32 s39, s11, 0
	s_add_u32 s40, s10, 0x8400
	s_addc_u32 s41, s11, 0
	s_add_u32 s42, s10, 0x8500
	s_addc_u32 s43, s11, 0
	s_add_u32 s54, s10, 0x8600
	s_addc_u32 s55, s11, 0
	s_add_u32 s64, s10, 0x8700
	s_addc_u32 s65, s11, 0
	s_add_u32 s78, s10, 0x8800
	s_addc_u32 s79, s11, 0
	s_add_u32 s80, s10, 0x8900
	s_addc_u32 s81, s11, 0
	s_mov_b32 s27, 1
	s_branch .LBB0_1123

; __device__ __forceinline__ unsigned xb_ld(unsigned* p)              { return __hip_atomic_load(p, __ATOMIC_RELAXED, __HIP_MEMORY_SCOPE_AGENT); }
; __device__ __forceinline__ unsigned xb_add(unsigned* p, unsigned v) { return __hip_atomic_fetch_add(p, v, __ATOMIC_RELAXED, __HIP_MEMORY_SCOPE_AGENT); }
; #define XB_SPIN(cond, bar) do { unsigned _sp = 0; while (cond) { __builtin_amdgcn_s_sleep(1); \
;     if ((++_sp & 255u) == 0u) { if (xb_ld(&(bar)[XB_TMO])) break; if (_sp > XB_SPIN_CAP) { atomicAdd(&(bar)[XB_TMO], 1u); break; } } } } while (0)
; __device__ __forceinline__ void grp_barrier(const XcdBarrier& b, unsigned gsz) {
;     ...
;         const unsigned old = xb_add(&bar[XB_XSUB(b.x)], 1u);
;         const bool early = (nx == 1u);
;         if (early) __builtin_amdgcn_fence(__ATOMIC_ACQUIRE, "agent");
;         const unsigned gen = old / nloc;
;         if (old + 1u == (gen + 1u) * nloc) {
;             if (nx > 1u) __builtin_amdgcn_fence(__ATOMIC_RELEASE, "agent");
;             if (!early) asm volatile("s_waitcnt vmcnt(0)" ::: "memory");
;             if (!early) {
;             const unsigned og = xb_add(&bar[XB_TOP], 1u);
;             const unsigned tg = og / nx;
;             if (og + 1u == (tg + 1u) * nx) xb_add(&bar[XB_TOPGEN], 1u);
;             else XB_SPIN(xb_ld(&bar[XB_TOPGEN]) == tg, bar);
;             }
;             if (!early) __builtin_amdgcn_fence(__ATOMIC_ACQUIRE, "agent");
;             xb_add(&bar[XB_XGEN(b.x)], 1u);
;             asm volatile("s_waitcnt vmcnt(0)" ::: "memory");
;         } else {
;             XB_SPIN(xb_ld(&bar[XB_XGEN(b.x)]) == gen, bar);
.LBB0_1137:
	s_or_b64 exec, exec, s[16:17]
	s_waitcnt lgkmcnt(0)
	v_cmp_ne_u32_e64 s[4:5], 1, v4
	s_waitcnt vmcnt(0)
	v_readfirstlane_b32 s3, v6
	s_and_b64 vcc, exec, s[4:5]
	s_cbranch_vccnz .LBB0_1139
.LBB0_1139:
	v_cvt_f32_u32_e32 v6, v5
	v_add_u32_e32 v7, s3, v3
	v_sub_u32_e32 v3, 0, v5
	v_rcp_iflag_f32_e32 v6, v6
	s_nop 0
	v_mul_f32_e32 v6, 0x4f7ffffe, v6
	v_cvt_u32_f32_e32 v6, v6
	v_mul_lo_u32 v3, v3, v6
	v_mul_hi_u32 v3, v6, v3
	v_add_u32_e32 v3, v6, v3
	v_mul_hi_u32 v3, v7, v3
	v_mul_lo_u32 v6, v3, v5
	v_sub_u32_e32 v6, v7, v6
	v_add_u32_e32 v8, 1, v3
	v_cmp_ge_u32_e32 vcc, v6, v5
	s_nop 1
	v_cndmask_b32_e32 v3, v3, v8, vcc
	v_sub_u32_e32 v8, v6, v5
	v_cndmask_b32_e32 v6, v6, v8, vcc
	v_add_u32_e32 v8, 1, v3
	v_cmp_ge_u32_e32 vcc, v6, v5
	v_add_u32_e32 v6, 1, v7
	s_nop 0
	v_cndmask_b32_e32 v3, v3, v8, vcc
	v_mul_lo_u32 v7, v5, v3
	v_add_u32_e32 v5, v7, v5
	v_cmp_ne_u32_e32 vcc, v6, v5
	s_and_saveexec_b64 s[16:17], vcc
	s_xor_b64 s[16:17], exec, s[16:17]
	s_cbranch_execz .LBB0_1155
	global_load_dword v4, v203, s[12:13] offset:1024 sc1
	s_add_u32 s22, s12, 0x2400
	s_addc_u32 s23, s13, 0
	s_waitcnt vmcnt(0)
	v_cmp_eq_u32_e32 vcc, v4, v3
	s_and_saveexec_b64 s[18:19], vcc
	s_cbranch_execz .LBB0_1152
	s_add_u32 s20, s10, 0x7800
	s_addc_u32 s21, s11, 0
	s_mov_b32 s3, 1
	s_mov_b64 s[24:25], 0
	s_branch .LBB0_1143

; __device__ __forceinline__ void grp_barrier(const XcdBarrier& b, unsigned gsz) {
;     asm volatile("s_waitcnt vmcnt(0)" ::: "memory");
;     __syncthreads();
;     if (threadIdx.x == 0) {
;         unsigned* bar = b.bar;
;         __builtin_amdgcn_s_waitcnt(0);
;         unsigned nloc = b.st[0], nx = b.st[1];
;         if (nloc == 0u) { grp_barrier_complete(bar, b.x, gsz, nloc, nx); b.st[0] = nloc; b.st[1] = nx; }
.LBB0_1195:
	s_mov_b64 s[4:5], s[48:49]
	s_mov_b32 s10, s2
	s_getreg_b32 s3, hwreg(HW_REG_XCC_ID, 0, 4)
	s_waitcnt vmcnt(0)
	v_readfirstlane_b32 s0, v0
	s_nop 3
	s_cmp_lt_u32 s0, 64
	s_cbranch_scc0 .Lgb_noinv8
	buffer_inv sc1
.Lgb_noinv8:
	s_barrier
	s_and_saveexec_b64 s[0:1], s[88:89]
	s_cbranch_execz .LBB0_1255
	s_load_dwordx2 s[4:5], s[4:5], 0x110
	s_and_b32 s10, s10, 7
	v_readlane_b32 s11, v250, 4
	s_mulk_i32 s10, 0x3600
	s_waitcnt lgkmcnt(0)
	v_mov_b32_e32 v3, s11
	ds_read_b32 v5, v3
	s_add_u32 s10, s4, s10
	v_readlane_b32 s4, v250, 5
	s_addc_u32 s11, s5, 0
	s_and_b32 s3, s3, 15
	v_mov_b32_e32 v3, s4
	ds_read_b32 v4, v3
	s_waitcnt lgkmcnt(1)
	v_cmp_ne_u32_e32 vcc, 0, v5
	s_cbranch_vccnz .LBB0_1211
	s_add_u32 s4, s10, 0x7800
	s_addc_u32 s5, s11, 0
	s_add_u32 s12, s10, 0x7a00
	s_addc_u32 s13, s11, 0
	s_add_u32 s14, s10, 0x7b00
	s_addc_u32 s15, s11, 0
	s_add_u32 s16, s10, 0x7c00
	s_addc_u32 s17, s11, 0
	s_add_u32 s18, s10, 0x7d00
	s_addc_u32 s19, s11, 0
	s_add_u32 s20, s10, 0x7e00
	s_addc_u32 s21, s11, 0
	s_add_u32 s22, s10, 0x7f00
	s_addc_u32 s23, s11, 0
	s_add_u32 s24, s10, 0x8000
	s_addc_u32 s25, s11, 0
	s_add_u32 s28, s10, 0x8100
	s_addc_u32 s29, s11, 0
	s_add_u32 s30, s10, 0x8200
	s_addc_u32 s31, s11, 0
	s_add_u32 s36, s10, 0x8300
	s_addc_u32 s37, s11, 0
	s_add_u32 s38, s10, 0x8400
	s_addc_u32 s39, s11, 0
	s_add_u32 s40, s10, 0x8500
	s_addc_u32 s41, s11, 0
	s_add_u32 s42, s10, 0x8600
	s_addc_u32 s43, s11, 0
	s_add_u32 s54, s10, 0x8700
	s_addc_u32 s55, s11, 0
	s_add_u32 s64, s10, 0x8800
	s_addc_u32 s65, s11, 0
	s_add_u32 s78, s10, 0x8900
	s_addc_u32 s79, s11, 0
	s_mov_b32 s27, 1
	s_branch .LBB0_1199

; __device__ __forceinline__ unsigned xb_ld(unsigned* p)              { return __hip_atomic_load(p, __ATOMIC_RELAXED, __HIP_MEMORY_SCOPE_AGENT); }
; __device__ __forceinline__ unsigned xb_add(unsigned* p, unsigned v) { return __hip_atomic_fetch_add(p, v, __ATOMIC_RELAXED, __HIP_MEMORY_SCOPE_AGENT); }
; #define XB_SPIN(cond, bar) do { unsigned _sp = 0; while (cond) { __builtin_amdgcn_s_sleep(1); \
;     if ((++_sp & 255u) == 0u) { if (xb_ld(&(bar)[XB_TMO])) break; if (_sp > XB_SPIN_CAP) { atomicAdd(&(bar)[XB_TMO], 1u); break; } } } } while (0)
; __device__ __forceinline__ void grp_barrier(const XcdBarrier& b, unsigned gsz) {
;     ...
;         const unsigned old = xb_add(&bar[XB_XSUB(b.x)], 1u);
;         const bool early = (nx == 1u);
;         if (early) __builtin_amdgcn_fence(__ATOMIC_ACQUIRE, "agent");
;         const unsigned gen = old / nloc;
;         if (old + 1u == (gen + 1u) * nloc) {
;             if (nx > 1u) __builtin_amdgcn_fence(__ATOMIC_RELEASE, "agent");
;             if (!early) asm volatile("s_waitcnt vmcnt(0)" ::: "memory");
;             if (!early) {
;             const unsigned og = xb_add(&bar[XB_TOP], 1u);
;             const unsigned tg = og / nx;
;             if (og + 1u == (tg + 1u) * nx) xb_add(&bar[XB_TOPGEN], 1u);
;             else XB_SPIN(xb_ld(&bar[XB_TOPGEN]) == tg, bar);
;             }
;             if (!early) __builtin_amdgcn_fence(__ATOMIC_ACQUIRE, "agent");
;             xb_add(&bar[XB_XGEN(b.x)], 1u);
;             asm volatile("s_waitcnt vmcnt(0)" ::: "memory");
;         } else {
;             XB_SPIN(xb_ld(&bar[XB_XGEN(b.x)]) == gen, bar);
.LBB0_1213:
	s_or_b64 exec, exec, s[14:15]
	s_waitcnt lgkmcnt(0)
	v_cmp_ne_u32_e64 s[4:5], 1, v4
	s_waitcnt vmcnt(0)
	v_readfirstlane_b32 s3, v6
	s_and_b64 vcc, exec, s[4:5]
	s_cbranch_vccnz .LBB0_1215
.LBB0_1215:
	v_cvt_f32_u32_e32 v6, v5
	v_add_u32_e32 v7, s3, v3
	v_sub_u32_e32 v3, 0, v5
	v_rcp_iflag_f32_e32 v6, v6
	s_nop 0
	v_mul_f32_e32 v6, 0x4f7ffffe, v6
	v_cvt_u32_f32_e32 v6, v6
	v_mul_lo_u32 v3, v3, v6
	v_mul_hi_u32 v3, v6, v3
	v_add_u32_e32 v3, v6, v3
	v_mul_hi_u32 v3, v7, v3
	v_mul_lo_u32 v6, v3, v5
	v_sub_u32_e32 v6, v7, v6
	v_add_u32_e32 v8, 1, v3
	v_cmp_ge_u32_e32 vcc, v6, v5
	s_nop 1
	v_cndmask_b32_e32 v3, v3, v8, vcc
	v_sub_u32_e32 v8, v6, v5
	v_cndmask_b32_e32 v6, v6, v8, vcc
	v_add_u32_e32 v8, 1, v3
	v_cmp_ge_u32_e32 vcc, v6, v5
	v_add_u32_e32 v6, 1, v7
	s_nop 0
	v_cndmask_b32_e32 v3, v3, v8, vcc
	v_mul_lo_u32 v7, v5, v3
	v_add_u32_e32 v5, v7, v5
	v_cmp_ne_u32_e32 vcc, v6, v5
	s_and_saveexec_b64 s[14:15], vcc
	s_xor_b64 s[14:15], exec, s[14:15]
	s_cbranch_execz .LBB0_1231
	global_load_dword v4, v203, s[12:13] offset:1024 sc1
	s_add_u32 s20, s12, 0x2400
	s_addc_u32 s21, s13, 0
	s_waitcnt vmcnt(0)
	v_cmp_eq_u32_e32 vcc, v4, v3
	s_and_saveexec_b64 s[16:17], vcc
	s_cbranch_execz .LBB0_1228
	s_add_u32 s18, s10, 0x7800
	s_addc_u32 s19, s11, 0
	s_mov_b32 s3, 1
	s_mov_b64 s[22:23], 0
	s_branch .LBB0_1219

; __device__ __forceinline__ void grp_barrier(const XcdBarrier& b, unsigned gsz) {
;     asm volatile("s_waitcnt vmcnt(0)" ::: "memory");
;     __syncthreads();
;     if (threadIdx.x == 0) {
;         unsigned* bar = b.bar;
;         __builtin_amdgcn_s_waitcnt(0);
;         unsigned nloc = b.st[0], nx = b.st[1];
;         if (nloc == 0u) { grp_barrier_complete(bar, b.x, gsz, nloc, nx); b.st[0] = nloc; b.st[1] = nx; }
.LBB0_1309:
	s_or_b64 exec, exec, s[4:5]
	s_mov_b64 s[4:5], s[48:49]
	s_mov_b32 s8, s2
	s_getreg_b32 s3, hwreg(HW_REG_XCC_ID, 0, 4)
	s_waitcnt vmcnt(0)
	v_readfirstlane_b32 s0, v0
	s_nop 3
	s_cmp_lt_u32 s0, 64
	s_cbranch_scc0 .Lgb_noinv9
	buffer_inv sc1
.Lgb_noinv9:
	s_barrier
	s_and_saveexec_b64 s[0:1], s[88:89]
	s_cbranch_execz .LBB0_1369
	s_load_dwordx2 s[4:5], s[4:5], 0x110
	s_and_b32 s8, s8, 7
	v_readlane_b32 s9, v250, 4
	s_mulk_i32 s8, 0x3600
	s_waitcnt lgkmcnt(0)
	v_mov_b32_e32 v3, s9
	ds_read_b32 v5, v3
	s_add_u32 s8, s4, s8
	v_readlane_b32 s4, v250, 5
	s_addc_u32 s9, s5, 0
	s_and_b32 s3, s3, 15
	v_mov_b32_e32 v3, s4
	ds_read_b32 v4, v3
	s_waitcnt lgkmcnt(1)
	v_cmp_ne_u32_e32 vcc, 0, v5
	s_cbranch_vccnz .LBB0_1325
	s_add_u32 s4, s8, 0x7800
	s_addc_u32 s5, s9, 0
	s_add_u32 s10, s8, 0x7a00
	s_addc_u32 s11, s9, 0
	s_add_u32 s12, s8, 0x7b00
	s_addc_u32 s13, s9, 0
	s_add_u32 s14, s8, 0x7c00
	s_addc_u32 s15, s9, 0
	s_add_u32 s16, s8, 0x7d00
	s_addc_u32 s17, s9, 0
	s_add_u32 s18, s8, 0x7e00
	s_addc_u32 s19, s9, 0
	s_add_u32 s20, s8, 0x7f00
	s_addc_u32 s21, s9, 0
	s_add_u32 s22, s8, 0x8000
	s_addc_u32 s23, s9, 0
	s_add_u32 s24, s8, 0x8100
	s_addc_u32 s25, s9, 0
	s_add_u32 s28, s8, 0x8200
	s_addc_u32 s29, s9, 0
	s_add_u32 s30, s8, 0x8300
	s_addc_u32 s31, s9, 0
	s_add_u32 s36, s8, 0x8400
	s_addc_u32 s37, s9, 0
	s_add_u32 s38, s8, 0x8500
	s_addc_u32 s39, s9, 0
	s_add_u32 s40, s8, 0x8600
	s_addc_u32 s41, s9, 0
	s_add_u32 s42, s8, 0x8700
	s_addc_u32 s43, s9, 0
	s_add_u32 s54, s8, 0x8800
	s_addc_u32 s55, s9, 0
	s_add_u32 s64, s8, 0x8900
	s_addc_u32 s65, s9, 0
	s_mov_b32 s27, 1
	s_branch .LBB0_1313

; __device__ __forceinline__ unsigned xb_ld(unsigned* p)              { return __hip_atomic_load(p, __ATOMIC_RELAXED, __HIP_MEMORY_SCOPE_AGENT); }
; __device__ __forceinline__ unsigned xb_add(unsigned* p, unsigned v) { return __hip_atomic_fetch_add(p, v, __ATOMIC_RELAXED, __HIP_MEMORY_SCOPE_AGENT); }
; #define XB_SPIN(cond, bar) do { unsigned _sp = 0; while (cond) { __builtin_amdgcn_s_sleep(1); \
;     if ((++_sp & 255u) == 0u) { if (xb_ld(&(bar)[XB_TMO])) break; if (_sp > XB_SPIN_CAP) { atomicAdd(&(bar)[XB_TMO], 1u); break; } } } } while (0)
; __device__ __forceinline__ void grp_barrier(const XcdBarrier& b, unsigned gsz) {
;     ...
;         const unsigned old = xb_add(&bar[XB_XSUB(b.x)], 1u);
;         const bool early = (nx == 1u);
;         if (early) __builtin_amdgcn_fence(__ATOMIC_ACQUIRE, "agent");
;         const unsigned gen = old / nloc;
;         if (old + 1u == (gen + 1u) * nloc) {
;             if (nx > 1u) __builtin_amdgcn_fence(__ATOMIC_RELEASE, "agent");
;             if (!early) asm volatile("s_waitcnt vmcnt(0)" ::: "memory");
;             if (!early) {
;             const unsigned og = xb_add(&bar[XB_TOP], 1u);
;             const unsigned tg = og / nx;
;             if (og + 1u == (tg + 1u) * nx) xb_add(&bar[XB_TOPGEN], 1u);
;             else XB_SPIN(xb_ld(&bar[XB_TOPGEN]) == tg, bar);
;             }
;             if (!early) __builtin_amdgcn_fence(__ATOMIC_ACQUIRE, "agent");
;             xb_add(&bar[XB_XGEN(b.x)], 1u);
;             asm volatile("s_waitcnt vmcnt(0)" ::: "memory");
;         } else {
;             XB_SPIN(xb_ld(&bar[XB_XGEN(b.x)]) == gen, bar);
.LBB0_1327:
	s_or_b64 exec, exec, s[12:13]
	s_waitcnt lgkmcnt(0)
	v_cmp_ne_u32_e64 s[4:5], 1, v4
	s_waitcnt vmcnt(0)
	v_readfirstlane_b32 s3, v6
	s_and_b64 vcc, exec, s[4:5]
	s_cbranch_vccnz .LBB0_1329
.LBB0_1329:
	v_cvt_f32_u32_e32 v6, v5
	v_add_u32_e32 v7, s3, v3
	v_sub_u32_e32 v3, 0, v5
	v_rcp_iflag_f32_e32 v6, v6
	s_nop 0
	v_mul_f32_e32 v6, 0x4f7ffffe, v6
	v_cvt_u32_f32_e32 v6, v6
	v_mul_lo_u32 v3, v3, v6
	v_mul_hi_u32 v3, v6, v3
	v_add_u32_e32 v3, v6, v3
	v_mul_hi_u32 v3, v7, v3
	v_mul_lo_u32 v6, v3, v5
	v_sub_u32_e32 v6, v7, v6
	v_add_u32_e32 v8, 1, v3
	v_cmp_ge_u32_e32 vcc, v6, v5
	s_nop 1
	v_cndmask_b32_e32 v3, v3, v8, vcc
	v_sub_u32_e32 v8, v6, v5
	v_cndmask_b32_e32 v6, v6, v8, vcc
	v_add_u32_e32 v8, 1, v3
	v_cmp_ge_u32_e32 vcc, v6, v5
	v_add_u32_e32 v6, 1, v7
	s_nop 0
	v_cndmask_b32_e32 v3, v3, v8, vcc
	v_mul_lo_u32 v7, v5, v3
	v_add_u32_e32 v5, v7, v5
	v_cmp_ne_u32_e32 vcc, v6, v5
	s_and_saveexec_b64 s[12:13], vcc
	s_xor_b64 s[12:13], exec, s[12:13]
	s_cbranch_execz .LBB0_1345
	global_load_dword v4, v203, s[10:11] offset:1024 sc1
	s_add_u32 s18, s10, 0x2400
	s_addc_u32 s19, s11, 0
	s_waitcnt vmcnt(0)
	v_cmp_eq_u32_e32 vcc, v4, v3
	s_and_saveexec_b64 s[14:15], vcc
	s_cbranch_execz .LBB0_1342
	s_add_u32 s16, s8, 0x7800
	s_addc_u32 s17, s9, 0
	s_mov_b32 s3, 1
	s_mov_b64 s[20:21], 0
	s_branch .LBB0_1333

; #define LAS __attribute__((address_space(3)))
; template <int RA, int NP, int NS, int KT, class R8>
; DI void small_gemm(LAS unsigned char* lds, const bf16* __restrict__ A, const bf16* __restrict__ Bt, int K, int row_base, int col_base, const R8& e, int tid, int wave, int lane) {
;     ...
;     for (int st = 0; st < NT; ++st) {
;         asm volatile("s_waitcnt vmcnt(%0)" :: "n"((NS - 2) * L) : "memory");
;         __builtin_amdgcn_s_barrier();
;         asm volatile("" ::: "memory");
;         { const int nslot = (st + NS - 1) % NS; SG_STAGE(st + NS - 1, nslot); }
;         const LAS unsigned char* sb0 = lds + (st % NS) * STAGE;
; #pragma unroll
;         for (int t = 0; t < KT; ++t) {
;             const LAS unsigned char* sb = sb0 + t * SUB;
;             bf16x8 af[RA][2], bfr[NP][2][2];
; #pragma unroll
;             for (int ra = 0; ra < RA; ++ra) { af[ra][0] = *(const LAS bf16x8*)(sb + aoff[ra]); af[ra][1] = *(const LAS bf16x8*)(sb + aoff[ra] + 1024); }
; #pragma unroll
;             for (int np = 0; np < NP; ++np)
; #pragma unroll
;                 for (int n = 0; n < 2; ++n) { bfr[np][n][0] = *(const LAS bf16x8*)(sb + boff[np][n]); bfr[np][n][1] = *(const LAS bf16x8*)(sb + boff[np][n] + 1024); }
; #pragma unroll
;             for (int ks = 0; ks < 2; ++ks)
; #pragma unroll
;                 for (int ra = 0; ra < RA; ++ra)
; #pragma unroll
;                     for (int np = 0; np < NP; ++np) { acc[ra][np][0] = __builtin_amdgcn_mfma_f32_16x16x32_bf16(bfr[np][0][ks], af[ra][ks], acc[ra][np][0], 0, 0, 0); acc[ra][np][1] = __builtin_amdgcn_mfma_f32_16x16x32_bf16(bfr[np][1][ks], af[ra][ks], acc[ra][np][1], 0, 0, 0); }
;         }
;     }
.LBB0_1388:
	s_mul_i32 s15, s7, 0xab
	s_bfe_u32 s15, s15, 0x70009
	s_mul_i32 s15, s15, 3
	s_sub_i32 s15, s7, s15
	s_and_b32 s15, s15, 0xff
	s_and_b32 s16, s10, 0x3c0
	s_mul_i32 s15, s15, 0xa000
	s_lshl_b32 s34, s16, 1
	s_add_i32 s15, s6, s15
	s_waitcnt vmcnt(5)
	s_barrier
	v_lshl_add_u64 v[52:53], v[42:43], 0, s[34:35]
	s_mov_b32 m0, s15
	v_lshl_add_u64 v[54:55], v[40:41], 0, s[34:35]
	global_load_lds_dwordx4 v[52:53], off
	s_add_i32 m0, s15, 0x2000
	v_lshl_add_u64 v[56:57], v[54:55], 0, s[58:59]
	global_load_lds_dwordx4 v[54:55], off
	s_add_i32 m0, s15, 0x4000
	v_lshl_add_u64 v[58:59], v[54:55], 0, s[50:51]
	global_load_lds_dwordx4 v[56:57], off
	s_add_i32 m0, s15, 0x6000
	v_lshl_add_u64 v[60:61], v[54:55], 0, s[60:61]
	global_load_lds_dwordx4 v[58:59], off
	s_add_i32 m0, s15, 0x8000
	s_mul_hi_u32 s14, s11, 0xaaaaaaab
	global_load_lds_dwordx4 v[60:61], off
	s_lshr_b32 s14, s14, 1
	s_mul_i32 s14, s14, 0x1e000
	s_add_i32 s18, s8, s9
	v_subrev_u32_e32 v62, s14, v48
	s_add_i32 s17, s9, 0
	v_subrev_u32_e32 v63, s14, v51
	v_subrev_u32_e32 v64, s14, v49
	v_add_u32_e32 v74, s18, v62
	v_add_u32_e32 v72, s17, v64
	v_add_u32_e32 v73, s17, v63
	ds_read_b128 v[52:55], v74 offset:8192
	ds_read_b128 v[56:59], v72
	ds_read_b128 v[60:63], v74 offset:10240
	ds_read_b128 v[64:67], v74 offset:12288
	ds_read_b128 v[68:71], v74 offset:14336
	s_waitcnt lgkmcnt(0)
	v_mfma_f32_16x16x32_bf16 v[28:31], v[52:55], v[56:59], v[28:31]
	s_add_i32 s11, s11, 1
	s_add_i32 s9, s9, 0xa000
	s_add_i32 s10, s10, 64
	v_mfma_f32_16x16x32_bf16 v[32:35], v[60:63], v[56:59], v[32:35]
	s_add_i32 s7, s7, 1
	s_cmp_lg_u32 s9, 0xa0000
	v_mfma_f32_16x16x32_bf16 v[20:23], v[64:67], v[56:59], v[20:23]
	v_mfma_f32_16x16x32_bf16 v[24:27], v[68:71], v[56:59], v[24:27]
	ds_read_b128 v[56:59], v73
	s_waitcnt lgkmcnt(0)
	v_mfma_f32_16x16x32_bf16 v[12:15], v[52:55], v[56:59], v[12:15]
	v_subrev_u32_e32 v52, s14, v50
	v_add_u32_e32 v73, s17, v52
	ds_read_b128 v[52:55], v74 offset:9216
	v_mfma_f32_16x16x32_bf16 v[16:19], v[60:63], v[56:59], v[16:19]
	ds_read_b128 v[60:63], v74 offset:11264
	v_mfma_f32_16x16x32_bf16 v[4:7], v[64:67], v[56:59], v[4:7]
	ds_read_b128 v[64:67], v74 offset:13312
	v_mfma_f32_16x16x32_bf16 v[8:11], v[68:71], v[56:59], v[8:11]
	ds_read_b128 v[68:71], v74 offset:15360
	ds_read_b128 v[56:59], v72 offset:1024
	s_waitcnt lgkmcnt(0)
	v_mfma_f32_16x16x32_bf16 v[28:31], v[52:55], v[56:59], v[28:31]
	v_mfma_f32_16x16x32_bf16 v[32:35], v[60:63], v[56:59], v[32:35]
	v_mfma_f32_16x16x32_bf16 v[20:23], v[64:67], v[56:59], v[20:23]
	v_mfma_f32_16x16x32_bf16 v[24:27], v[68:71], v[56:59], v[24:27]
	ds_read_b128 v[56:59], v73
	s_waitcnt lgkmcnt(0)
	v_mfma_f32_16x16x32_bf16 v[12:15], v[52:55], v[56:59], v[12:15]
	v_mfma_f32_16x16x32_bf16 v[16:19], v[60:63], v[56:59], v[16:19]
	v_mfma_f32_16x16x32_bf16 v[4:7], v[64:67], v[56:59], v[4:7]
	v_mfma_f32_16x16x32_bf16 v[8:11], v[68:71], v[56:59], v[8:11]
	s_cbranch_scc1 .LBB0_1388
; DI u32x4 pack8(const f32x4 v0, const f32x4 v1) { u32x4 w; w.x = pk2(v0[0], v0[1]); w.y = pk2(v0[2], v0[3]); w.z = pk2(v1[0], v1[1]); w.w = pk2(v1[2], v1[3]); return w; }
;     DI void row8(int row, int col, f32x4 v0, f32x4 v1, float, int fq) const { row8p(row, col, v0, v1, pre(row, col), fq); }
;     DI void row8(int row, int col, f32x4 v0, f32x4 v1, float r, int) const {
;         v0 = v0 * r; v1 = v1 * r;
;         if (MODE == 1) {
; #pragma unroll
;             for (int j = 0; j < 4; ++j) { const float a = v0[j] > 0.f ? v0[j] : 0.f, b = v1[j] > 0.f ? v1[j] : 0.f; v0[j] = a * a; v1[j] = b * b; } }
;         *(u32x4*)(O + (size_t)row * ldc + col) = pack8(v0, v1);
; __device__ __forceinline__ void grp_barrier(const XcdBarrier& b, unsigned gsz) {
;     asm volatile("s_waitcnt vmcnt(0)" ::: "memory");
;     __syncthreads();
;     if (threadIdx.x == 0) {
;         unsigned* bar = b.bar;
;         __builtin_amdgcn_s_waitcnt(0);
;         unsigned nloc = b.st[0], nx = b.st[1];
;         if (nloc == 0u) { grp_barrier_complete(bar, b.x, gsz, nloc, nx); b.st[0] = nloc; b.st[1] = nx; }
	v_add_f32_e32 v41, v44, v45
	v_add_f32_e32 v40, v46, v47
	v_mov_b32_e32 v42, v41
	v_mov_b32_e32 v43, v40
	s_nop 0
	v_permlane32_swap_b32_e32 v41, v42
	v_permlane32_swap_b32_e32 v40, v43
	v_add_f32_e32 v40, v40, v43
	v_add_f32_e32 v41, v41, v42
	v_fmamk_f32 v40, v40, 0x3a800000, v1
	v_fmamk_f32 v41, v41, 0x3a800000, v1
	v_rsq_f32_e32 v40, v40
	v_rsq_f32_e32 v42, v41
	s_lshl_b32 s6, s13, 2
	s_sub_i32 s6, s12, s6
	s_lshl_b32 s6, s6, 6
	v_pk_mul_f32 v[30:31], v[42:43], v[30:31] op_sel_hi:[0,1]
	v_pk_mul_f32 v[28:29], v[42:43], v[28:29] op_sel_hi:[0,1]
	v_pk_mul_f32 v[32:33], v[42:43], v[32:33] op_sel_hi:[0,1]
	v_pk_mul_f32 v[14:15], v[40:41], v[14:15] op_sel_hi:[0,1]
	v_pk_mul_f32 v[12:13], v[40:41], v[12:13] op_sel_hi:[0,1]
	v_pk_mul_f32 v[16:17], v[40:41], v[16:17] op_sel_hi:[0,1]
	s_add_i32 s6, s6, s3
	v_pk_mul_f32 v[34:35], v[42:43], v[34:35] op_sel_hi:[0,1]
	v_max_f32_e32 v29, 0, v29
	v_max_f32_e32 v28, 0, v28
	v_max_f32_e32 v33, 0, v33
	v_max_f32_e32 v32, 0, v32
	v_max_f32_e32 v31, 0, v31
	v_max_f32_e32 v30, 0, v30
	v_max_f32_e32 v13, 0, v13
	v_max_f32_e32 v12, 0, v12
	v_max_f32_e32 v17, 0, v17
	v_max_f32_e32 v16, 0, v16
	v_max_f32_e32 v15, 0, v15
	v_max_f32_e32 v14, 0, v14
	v_or_b32_e32 v44, s6, v3
	v_pk_mul_f32 v[28:29], v[28:29], v[28:29]
	v_pk_mul_f32 v[32:33], v[32:33], v[32:33]
	v_pk_mul_f32 v[30:31], v[30:31], v[30:31]
	v_max_f32_e32 v35, 0, v35
	v_max_f32_e32 v34, 0, v34
	v_pk_mul_f32 v[22:23], v[42:43], v[22:23] op_sel_hi:[0,1]
	v_pk_mul_f32 v[20:21], v[42:43], v[20:21] op_sel_hi:[0,1]
	v_pk_mul_f32 v[26:27], v[42:43], v[26:27] op_sel_hi:[0,1]
	v_pk_mul_f32 v[24:25], v[42:43], v[24:25] op_sel_hi:[0,1]
	v_pk_mul_f32 v[18:19], v[40:41], v[18:19] op_sel_hi:[0,1]
	v_pk_mul_f32 v[12:13], v[12:13], v[12:13]
	v_pk_mul_f32 v[16:17], v[16:17], v[16:17]
	v_pk_mul_f32 v[14:15], v[14:15], v[14:15]
	v_pk_mul_f32 v[6:7], v[40:41], v[6:7] op_sel_hi:[0,1]
	v_pk_mul_f32 v[4:5], v[40:41], v[4:5] op_sel_hi:[0,1]
	v_pk_mul_f32 v[10:11], v[40:41], v[10:11] op_sel_hi:[0,1]
	v_pk_mul_f32 v[8:9], v[40:41], v[8:9] op_sel_hi:[0,1]
	v_pk_mul_f32 v[34:35], v[34:35], v[34:35]
	v_cvt_pk_bf16_f32 v28, v28, v29
	v_cvt_pk_bf16_f32 v29, v30, v31
	v_cvt_pk_bf16_f32 v30, v32, v33
	v_lshlrev_b64 v[32:33], 13, v[38:39]
	v_ashrrev_i32_e32 v45, 31, v44
	v_max_f32_e32 v21, 0, v21
	v_max_f32_e32 v20, 0, v20
	v_max_f32_e32 v25, 0, v25
	v_max_f32_e32 v24, 0, v24
	v_max_f32_e32 v23, 0, v23
	v_max_f32_e32 v22, 0, v22
	v_max_f32_e32 v27, 0, v27
	v_max_f32_e32 v26, 0, v26
	v_max_f32_e32 v19, 0, v19
	v_max_f32_e32 v18, 0, v18
	v_cvt_pk_bf16_f32 v12, v12, v13
	v_cvt_pk_bf16_f32 v13, v14, v15
	v_cvt_pk_bf16_f32 v14, v16, v17
	v_lshlrev_b64 v[16:17], 13, v[36:37]
	v_max_f32_e32 v5, 0, v5
	v_max_f32_e32 v4, 0, v4
	v_max_f32_e32 v9, 0, v9
	v_max_f32_e32 v8, 0, v8
	v_max_f32_e32 v7, 0, v7
	v_max_f32_e32 v6, 0, v6
	v_max_f32_e32 v11, 0, v11
	v_max_f32_e32 v10, 0, v10
	v_cvt_pk_bf16_f32 v31, v34, v35
	v_lshl_add_u64 v[32:33], s[4:5], 0, v[32:33]
	v_lshlrev_b64 v[34:35], 1, v[44:45]
	v_pk_mul_f32 v[20:21], v[20:21], v[20:21]
	v_pk_mul_f32 v[24:25], v[24:25], v[24:25]
	v_pk_mul_f32 v[22:23], v[22:23], v[22:23]
	v_pk_mul_f32 v[26:27], v[26:27], v[26:27]
	v_pk_mul_f32 v[18:19], v[18:19], v[18:19]
	v_lshl_add_u64 v[16:17], s[4:5], 0, v[16:17]
	v_pk_mul_f32 v[4:5], v[4:5], v[4:5]
	v_pk_mul_f32 v[8:9], v[8:9], v[8:9]
	v_pk_mul_f32 v[6:7], v[6:7], v[6:7]
	v_pk_mul_f32 v[10:11], v[10:11], v[10:11]
	v_lshl_add_u64 v[32:33], v[32:33], 0, v[34:35]
	v_cvt_pk_bf16_f32 v20, v20, v21
	v_cvt_pk_bf16_f32 v21, v22, v23
	v_cvt_pk_bf16_f32 v22, v24, v25
	v_cvt_pk_bf16_f32 v23, v26, v27
	v_cvt_pk_bf16_f32 v15, v18, v19
	v_lshl_add_u64 v[16:17], v[16:17], 0, v[34:35]
	v_cvt_pk_bf16_f32 v4, v4, v5
	v_cvt_pk_bf16_f32 v5, v6, v7
	v_cvt_pk_bf16_f32 v6, v8, v9
	v_cvt_pk_bf16_f32 v7, v10, v11
	s_mov_b64 s[4:5], s[48:49]
	s_mov_b32 s8, s2
	s_waitcnt vmcnt(0)
	s_barrier
	global_store_dwordx4 v[32:33], v[28:31], off
	global_store_dwordx4 v[32:33], v[20:23], off offset:64
	global_store_dwordx4 v[16:17], v[12:15], off
	global_store_dwordx4 v[16:17], v[4:7], off offset:64
	s_getreg_b32 s3, hwreg(HW_REG_XCC_ID, 0, 4)
	s_waitcnt vmcnt(0)
	s_waitcnt vmcnt(0)
	v_readfirstlane_b32 s6, v0
	s_nop 3
	s_cmp_lt_u32 s6, 64
	s_cbranch_scc0 .Lgb_noinv10
	buffer_inv sc1
.Lgb_noinv10:
	s_barrier
	s_and_saveexec_b64 s[6:7], s[88:89]
	s_cbranch_execz .LBB0_1449
	s_load_dwordx2 s[4:5], s[4:5], 0x110
	s_and_b32 s8, s8, 7
	v_readlane_b32 s9, v250, 4
	s_mulk_i32 s8, 0x3600
	s_waitcnt lgkmcnt(0)
	v_mov_b32_e32 v3, s9
	ds_read_b32 v5, v3
	s_add_u32 s8, s4, s8
	v_readlane_b32 s4, v250, 5
	s_addc_u32 s9, s5, 0
	s_and_b32 s3, s3, 15
	v_mov_b32_e32 v3, s4
	ds_read_b32 v4, v3
	s_waitcnt lgkmcnt(1)
	v_cmp_ne_u32_e32 vcc, 0, v5
	s_cbranch_vccnz .LBB0_1405
	s_add_u32 s4, s8, 0x7800
	s_addc_u32 s5, s9, 0
	s_add_u32 s10, s8, 0x7a00
	s_addc_u32 s11, s9, 0
	s_add_u32 s12, s8, 0x7b00
	s_addc_u32 s13, s9, 0
	s_add_u32 s14, s8, 0x7c00
	s_addc_u32 s15, s9, 0
	s_add_u32 s16, s8, 0x7d00
	s_addc_u32 s17, s9, 0
	s_add_u32 s18, s8, 0x7e00
	s_addc_u32 s19, s9, 0
	s_add_u32 s20, s8, 0x7f00
	s_addc_u32 s21, s9, 0
	s_add_u32 s22, s8, 0x8000
	s_addc_u32 s23, s9, 0
	s_add_u32 s24, s8, 0x8100
	s_addc_u32 s25, s9, 0
	s_add_u32 s28, s8, 0x8200
	s_addc_u32 s29, s9, 0
	s_add_u32 s30, s8, 0x8300
	s_addc_u32 s31, s9, 0
	s_add_u32 s36, s8, 0x8400
	s_addc_u32 s37, s9, 0
	s_add_u32 s38, s8, 0x8500
	s_addc_u32 s39, s9, 0
	s_add_u32 s40, s8, 0x8600
	s_addc_u32 s41, s9, 0
	s_add_u32 s42, s8, 0x8700
	s_addc_u32 s43, s9, 0
	s_add_u32 s54, s8, 0x8800
	s_addc_u32 s55, s9, 0
	s_add_u32 s64, s8, 0x8900
	s_addc_u32 s65, s9, 0
	s_mov_b32 s27, 1
	s_branch .LBB0_1393

; __device__ __forceinline__ unsigned xb_ld(unsigned* p)              { return __hip_atomic_load(p, __ATOMIC_RELAXED, __HIP_MEMORY_SCOPE_AGENT); }
; __device__ __forceinline__ unsigned xb_add(unsigned* p, unsigned v) { return __hip_atomic_fetch_add(p, v, __ATOMIC_RELAXED, __HIP_MEMORY_SCOPE_AGENT); }
; #define XB_SPIN(cond, bar) do { unsigned _sp = 0; while (cond) { __builtin_amdgcn_s_sleep(1); \
;     if ((++_sp & 255u) == 0u) { if (xb_ld(&(bar)[XB_TMO])) break; if (_sp > XB_SPIN_CAP) { atomicAdd(&(bar)[XB_TMO], 1u); break; } } } } while (0)
; __device__ __forceinline__ void grp_barrier(const XcdBarrier& b, unsigned gsz) {
;     ...
;         const unsigned old = xb_add(&bar[XB_XSUB(b.x)], 1u);
;         const bool early = (nx == 1u);
;         if (early) __builtin_amdgcn_fence(__ATOMIC_ACQUIRE, "agent");
;         const unsigned gen = old / nloc;
;         if (old + 1u == (gen + 1u) * nloc) {
;             if (nx > 1u) __builtin_amdgcn_fence(__ATOMIC_RELEASE, "agent");
;             if (!early) asm volatile("s_waitcnt vmcnt(0)" ::: "memory");
;             if (!early) {
;             const unsigned og = xb_add(&bar[XB_TOP], 1u);
;             const unsigned tg = og / nx;
;             if (og + 1u == (tg + 1u) * nx) xb_add(&bar[XB_TOPGEN], 1u);
;             else XB_SPIN(xb_ld(&bar[XB_TOPGEN]) == tg, bar);
;             }
;             if (!early) __builtin_amdgcn_fence(__ATOMIC_ACQUIRE, "agent");
;             xb_add(&bar[XB_XGEN(b.x)], 1u);
;             asm volatile("s_waitcnt vmcnt(0)" ::: "memory");
;         } else {
;             XB_SPIN(xb_ld(&bar[XB_XGEN(b.x)]) == gen, bar);
.LBB0_1407:
	s_or_b64 exec, exec, s[12:13]
	s_waitcnt lgkmcnt(0)
	v_cmp_ne_u32_e64 s[4:5], 1, v4
	s_waitcnt vmcnt(0)
	v_readfirstlane_b32 s3, v6
	s_and_b64 vcc, exec, s[4:5]
	s_cbranch_vccnz .LBB0_1409
.LBB0_1409:
	v_cvt_f32_u32_e32 v6, v5
	v_add_u32_e32 v7, s3, v3
	v_sub_u32_e32 v3, 0, v5
	v_rcp_iflag_f32_e32 v6, v6
	s_nop 0
	v_mul_f32_e32 v6, 0x4f7ffffe, v6
	v_cvt_u32_f32_e32 v6, v6
	v_mul_lo_u32 v3, v3, v6
	v_mul_hi_u32 v3, v6, v3
	v_add_u32_e32 v3, v6, v3
	v_mul_hi_u32 v3, v7, v3
	v_mul_lo_u32 v6, v3, v5
	v_sub_u32_e32 v6, v7, v6
	v_add_u32_e32 v8, 1, v3
	v_cmp_ge_u32_e32 vcc, v6, v5
	s_nop 1
	v_cndmask_b32_e32 v3, v3, v8, vcc
	v_sub_u32_e32 v8, v6, v5
	v_cndmask_b32_e32 v6, v6, v8, vcc
	v_add_u32_e32 v8, 1, v3
	v_cmp_ge_u32_e32 vcc, v6, v5
	v_add_u32_e32 v6, 1, v7
	s_nop 0
	v_cndmask_b32_e32 v3, v3, v8, vcc
	v_mul_lo_u32 v7, v5, v3
	v_add_u32_e32 v5, v7, v5
	v_cmp_ne_u32_e32 vcc, v6, v5
	s_and_saveexec_b64 s[12:13], vcc
	s_xor_b64 s[12:13], exec, s[12:13]
	s_cbranch_execz .LBB0_1425
	global_load_dword v4, v203, s[10:11] offset:1024 sc1
	s_add_u32 s18, s10, 0x2400
	s_addc_u32 s19, s11, 0
	s_waitcnt vmcnt(0)
	v_cmp_eq_u32_e32 vcc, v4, v3
	s_and_saveexec_b64 s[14:15], vcc
	s_cbranch_execz .LBB0_1422
	s_add_u32 s16, s8, 0x7800
	s_addc_u32 s17, s9, 0
	s_mov_b32 s3, 1
	s_mov_b64 s[20:21], 0
	s_branch .LBB0_1413

; __device__ __forceinline__ void grp_barrier(const XcdBarrier& b, unsigned gsz) {
;     asm volatile("s_waitcnt vmcnt(0)" ::: "memory");
;     __syncthreads();
;     if (threadIdx.x == 0) {
.Lgb_noinv11:
	s_barrier
	s_and_saveexec_b64 s[0:1], s[88:89]
	s_cbranch_execnz .LBB0_1504
	s_getpc_b64 s[98:99]

; __device__ __forceinline__ void grp_barrier(const XcdBarrier& b, unsigned gsz) {
;     ...
;     if (threadIdx.x == 0) {
;         unsigned* bar = b.bar;
;         __builtin_amdgcn_s_waitcnt(0);
;         unsigned nloc = b.st[0], nx = b.st[1];
;         if (nloc == 0u) { grp_barrier_complete(bar, b.x, gsz, nloc, nx); b.st[0] = nloc; b.st[1] = nx; }
.LBB0_1504:
	s_load_dwordx2 s[4:5], s[4:5], 0x110
	s_and_b32 s6, s6, 7
	v_readlane_b32 s7, v250, 4
	s_mulk_i32 s6, 0x3600
	s_waitcnt lgkmcnt(0)
	v_mov_b32_e32 v3, s7
	ds_read_b32 v5, v3
	s_add_u32 s6, s4, s6
	v_readlane_b32 s4, v250, 5
	s_addc_u32 s7, s5, 0
	s_and_b32 s3, s3, 15
	v_mov_b32_e32 v3, s4
	ds_read_b32 v4, v3
	s_waitcnt lgkmcnt(1)
	v_cmp_ne_u32_e32 vcc, 0, v5
	s_cbranch_vccnz .LBB0_1519
	s_add_u32 s4, s6, 0x7800
	s_addc_u32 s5, s7, 0
	s_add_u32 s8, s6, 0x7a00
	s_addc_u32 s9, s7, 0
	s_add_u32 s10, s6, 0x7b00
	s_addc_u32 s11, s7, 0
	s_add_u32 s12, s6, 0x7c00
	s_addc_u32 s13, s7, 0
	s_add_u32 s14, s6, 0x7d00
	s_addc_u32 s15, s7, 0
	s_add_u32 s16, s6, 0x7e00
	s_addc_u32 s17, s7, 0
	s_add_u32 s18, s6, 0x7f00
	s_addc_u32 s19, s7, 0
	s_add_u32 s20, s6, 0x8000
	s_addc_u32 s21, s7, 0
	s_add_u32 s22, s6, 0x8100
	s_addc_u32 s23, s7, 0
	s_add_u32 s24, s6, 0x8200
	s_addc_u32 s25, s7, 0
	s_add_u32 s28, s6, 0x8300
	s_addc_u32 s29, s7, 0
	s_add_u32 s30, s6, 0x8400
	s_addc_u32 s31, s7, 0
	s_add_u32 s36, s6, 0x8500
	s_addc_u32 s37, s7, 0
	s_add_u32 s38, s6, 0x8600
	s_addc_u32 s39, s7, 0
	s_add_u32 s40, s6, 0x8700
	s_addc_u32 s41, s7, 0
	s_add_u32 s42, s6, 0x8800
	s_addc_u32 s43, s7, 0
	s_add_u32 s54, s6, 0x8900
	s_addc_u32 s55, s7, 0
	s_mov_b32 s27, 1
	s_branch .LBB0_1507

; __device__ __forceinline__ unsigned xb_ld(unsigned* p)              { return __hip_atomic_load(p, __ATOMIC_RELAXED, __HIP_MEMORY_SCOPE_AGENT); }
; __device__ __forceinline__ unsigned xb_add(unsigned* p, unsigned v) { return __hip_atomic_fetch_add(p, v, __ATOMIC_RELAXED, __HIP_MEMORY_SCOPE_AGENT); }
; #define XB_SPIN(cond, bar) do { unsigned _sp = 0; while (cond) { __builtin_amdgcn_s_sleep(1); \
;     if ((++_sp & 255u) == 0u) { if (xb_ld(&(bar)[XB_TMO])) break; if (_sp > XB_SPIN_CAP) { atomicAdd(&(bar)[XB_TMO], 1u); break; } } } } while (0)
; __device__ __forceinline__ void grp_barrier(const XcdBarrier& b, unsigned gsz) {
;     ...
;         const unsigned old = xb_add(&bar[XB_XSUB(b.x)], 1u);
;         const bool early = (nx == 1u);
;         if (early) __builtin_amdgcn_fence(__ATOMIC_ACQUIRE, "agent");
;         const unsigned gen = old / nloc;
;         if (old + 1u == (gen + 1u) * nloc) {
;             if (nx > 1u) __builtin_amdgcn_fence(__ATOMIC_RELEASE, "agent");
;             if (!early) asm volatile("s_waitcnt vmcnt(0)" ::: "memory");
;             if (!early) {
;             const unsigned og = xb_add(&bar[XB_TOP], 1u);
;             const unsigned tg = og / nx;
;             if (og + 1u == (tg + 1u) * nx) xb_add(&bar[XB_TOPGEN], 1u);
;             else XB_SPIN(xb_ld(&bar[XB_TOPGEN]) == tg, bar);
;             }
;             if (!early) __builtin_amdgcn_fence(__ATOMIC_ACQUIRE, "agent");
;             xb_add(&bar[XB_XGEN(b.x)], 1u);
;             asm volatile("s_waitcnt vmcnt(0)" ::: "memory");
;         } else {
;             XB_SPIN(xb_ld(&bar[XB_XGEN(b.x)]) == gen, bar);
.LBB0_1521:
	s_or_b64 exec, exec, s[10:11]
	s_waitcnt lgkmcnt(0)
	v_cmp_ne_u32_e64 s[4:5], 1, v4
	s_waitcnt vmcnt(0)
	v_readfirstlane_b32 s3, v6
	s_and_b64 vcc, exec, s[4:5]
	s_cbranch_vccnz .LBB0_1523
.LBB0_1523:
	v_cvt_f32_u32_e32 v6, v5
	v_add_u32_e32 v7, s3, v3
	v_sub_u32_e32 v3, 0, v5
	v_rcp_iflag_f32_e32 v6, v6
	s_nop 0
	v_mul_f32_e32 v6, 0x4f7ffffe, v6
	v_cvt_u32_f32_e32 v6, v6
	v_mul_lo_u32 v3, v3, v6
	v_mul_hi_u32 v3, v6, v3
	v_add_u32_e32 v3, v6, v3
	v_mul_hi_u32 v3, v7, v3
	v_mul_lo_u32 v6, v3, v5
	v_sub_u32_e32 v6, v7, v6
	v_add_u32_e32 v8, 1, v3
	v_cmp_ge_u32_e32 vcc, v6, v5
	s_nop 1
	v_cndmask_b32_e32 v3, v3, v8, vcc
	v_sub_u32_e32 v8, v6, v5
	v_cndmask_b32_e32 v6, v6, v8, vcc
	v_add_u32_e32 v8, 1, v3
	v_cmp_ge_u32_e32 vcc, v6, v5
	v_add_u32_e32 v6, 1, v7
	s_nop 0
	v_cndmask_b32_e32 v3, v3, v8, vcc
	v_mul_lo_u32 v7, v5, v3
	v_add_u32_e32 v5, v7, v5
	v_cmp_ne_u32_e32 vcc, v6, v5
	s_and_saveexec_b64 s[10:11], vcc
	s_xor_b64 s[10:11], exec, s[10:11]
	s_cbranch_execz .LBB0_1539
	global_load_dword v4, v203, s[8:9] offset:1024 sc1
	s_add_u32 s16, s8, 0x2400
	s_addc_u32 s17, s9, 0
	s_waitcnt vmcnt(0)
	v_cmp_eq_u32_e32 vcc, v4, v3
	s_and_saveexec_b64 s[12:13], vcc
	s_cbranch_execz .LBB0_1536
	s_add_u32 s14, s6, 0x7800
	s_addc_u32 s15, s7, 0
	s_mov_b32 s3, 1
	s_mov_b64 s[18:19], 0
	s_branch .LBB0_1527
